# static priority raise for the younger co-resident workgroup inside the hand-scheduled GEMM k-loops (no per-burst toggling)
# speedup vs baseline: 1.0111x; 1.0068x over previous
; DEV int tid_() { int t = __builtin_amdgcn_workitem_id_x(); asm volatile("" : "+v"(t)); return t; }
; template <class Epi>
; DEV void gemm_tile(const bf16_t* __restrict__ A, int lda, const bf16_t* __restrict__ Bt, int ldb, int K, int tm, int tn, char* smem, const Epi& epi) {
;     const int tid = tid_(), lane = tid & 63, wid = tid >> 6, wr = wid >> 1, wc = wid & 1, fr = lane & 15, fq = lane >> 4;
;     bf16_t* As = (bf16_t*)smem;
;     bf16_t* Bs = As + 2 * 128 * 64;
;     const int lrow = tid >> 3, lcc = (tid & 7) * 8, lsw = (((tid & 7) ^ (lrow & 7)) * 8);
;     const bf16_t* Ag = A + (size_t)(tm * 128 + lrow) * lda + lcc;
;     const bf16_t* Bg = Bt + (size_t)(tn * 128 + lrow) * ldb + lcc;
;     f32x4 acc[4][4];
; #pragma unroll
;     for (int m = 0; m < 4; ++m)
; #pragma unroll
;         for (int n = 0; n < 4; ++n) acc[m][n] = (f32x4){0.f, 0.f, 0.f, 0.f};
;     const int gsw = (((tid & 7) ^ (lrow & 7)) * 8);
;     const bf16_t* Ad = A + (size_t)(tm * 128 + lrow) * lda + gsw;
;     const bf16_t* Bd = Bt + (size_t)(tn * 128 + lrow) * ldb + gsw;
;     char* Asb = (char*)As; char* Bsb = (char*)Bs;
;     ...
;     const int nk = K >> 6;
;     G_DMA(0, 0);
;     asm volatile("s_waitcnt vmcnt(0)" ::: "memory");
;     __syncthreads();
; template <class Epi>
; DEV void gemm_phase(const bf16_t* A, int lda, const bf16_t* Bt, int ldb, int K, int ntm, int ntn, bool skip_ctx, char* smem, const Epi& epi) {
;     ...
;             if (q < fullq) { const int tb = q / (R * 8), r = q - tb * (R * 8); tm = r >> 3; tn = tb * 8 + (r & 7); }
;             else { const int q2 = q - fullq; tm = q2 / w; tn = nfb * 8 + (q2 - tm * w); }
;             tm += xcd * R;
;             if (skip_ctx && ((tm * 128) % TT) >= SEQ) continue;
.LBB0_97:
	v_readlane_b32 s2, v253, 31
	s_add_i32 s62, s42, s2
	s_lshl_b32 s2, s62, 7
	s_mul_hi_i32 s3, s2, 0x38e38e39
	s_lshr_b32 s38, s3, 31
	s_ashr_i32 s3, s3, 9
	s_add_i32 s3, s3, s38
	s_mulk_i32 s3, 0x900
	s_sub_i32 s92, s2, s3
	s_cmpk_gt_i32 s92, 0x7ff
	s_cselect_b64 s[38:39], -1, 0
	s_and_b64 s[38:39], s[54:55], s[38:39]
	s_and_b64 vcc, exec, s[38:39]
	s_cbranch_vccnz .LBB0_92
	v_mov_b32_e32 v12, v163
	s_mov_b64 s[38:39], 0x10000
	v_ashrrev_i32_e32 v14, 3, v12
	v_add_u32_e32 v2, s2, v14
	v_lshl_add_u32 v4, s43, 7, v14
	v_ashrrev_i32_e32 v3, 31, v2
	v_ashrrev_i32_e32 v5, 31, v4
	s_waitcnt vmcnt(10)
	v_xor_b32_e32 v0, v14, v12
	v_lshlrev_b64 v[2:3], 11, v[2:3]
	v_lshlrev_b64 v[4:5], 11, v[4:5]
	v_lshlrev_b32_e32 v0, 4, v0
	v_lshl_add_u64 v[6:7], s[26:27], 0, v[2:3]
	v_lshl_add_u64 v[8:9], s[48:49], 0, v[4:5]
	v_and_b32_e32 v0, 0x70, v0
	v_lshl_add_u64 v[6:7], v[6:7], 0, v[0:1]
	v_lshl_add_u64 v[8:9], v[8:9], 0, v[0:1]
	v_lshlrev_b32_e32 v0, 4, v12
	v_add_u32_e32 v0, 16, v0
	v_add_u32_e32 v76, 0x8000, v0
	v_readfirstlane_b32 s2, v0
	s_mov_b32 m0, s2
	v_readfirstlane_b32 s2, v76
	v_add_u32_e32 v77, 0x1000, v0
	global_load_lds_dwordx4 v[6:7], off
	s_mov_b32 m0, s2
	v_readfirstlane_b32 s2, v77
	v_add_u32_e32 v78, 0x9000, v0
	global_load_lds_dwordx4 v[8:9], off
	v_lshl_add_u64 v[10:11], v[6:7], 0, s[38:39]
	s_mov_b32 m0, s2
	v_readfirstlane_b32 s2, v78
	v_add_u32_e32 v79, 0x2000, v0
	global_load_lds_dwordx4 v[10:11], off
	v_lshl_add_u64 v[10:11], v[8:9], 0, s[38:39]
	s_mov_b32 m0, s2
	s_mov_b64 s[38:39], 0x20000
	v_readfirstlane_b32 s2, v79
	v_add_u32_e32 v80, 0xa000, v0
	global_load_lds_dwordx4 v[10:11], off
	v_lshl_add_u64 v[10:11], v[6:7], 0, s[38:39]
	s_mov_b32 m0, s2
	v_readfirstlane_b32 s2, v80
	v_add_u32_e32 v81, 0x3000, v0
	global_load_lds_dwordx4 v[10:11], off
	v_lshl_add_u64 v[10:11], v[8:9], 0, s[38:39]
	s_mov_b32 m0, s2
	s_mov_b64 s[38:39], 0x30000
	v_readfirstlane_b32 s2, v81
	v_add_u32_e32 v82, 0xb000, v0
	global_load_lds_dwordx4 v[10:11], off
	v_lshl_add_u64 v[6:7], v[6:7], 0, s[38:39]
	s_mov_b32 m0, s2
	v_readfirstlane_b32 s2, v82
	global_load_lds_dwordx4 v[6:7], off
	v_lshl_add_u64 v[6:7], v[8:9], 0, s[38:39]
	s_mov_b32 m0, s2
	v_lshrrev_b32_e32 v13, 4, v12
	global_load_lds_dwordx4 v[6:7], off
	v_and_b32_e32 v75, 15, v12
	v_ashrrev_i32_e32 v84, 7, v12
	v_bfe_u32 v83, v12, 4, 2
	v_and_b32_e32 v8, 7, v12
	v_lshlrev_b32_e32 v6, 13, v84
	v_lshlrev_b32_e32 v7, 7, v75
	v_bitop3_b32 v9, v13, v8, 3 bitop3:0x6c
	v_bitop3_b32 v8, v83, v8, 4 bitop3:0x36
	v_add3_u32 v6, 16, v6, v7
	v_lshlrev_b32_e32 v9, 4, v9
	v_lshlrev_b32_e32 v8, 4, v8
	v_add_u32_e32 v85, v6, v9
	v_add_u32_e32 v87, v6, v8
	v_bitop3_b32 v6, v14, 7, v12 bitop3:0x48
	v_bfe_u32 v74, v12, 6, 1
	v_lshlrev_b32_e32 v6, 4, v6
	s_waitcnt vmcnt(0)
	v_lshlrev_b32_e32 v10, 13, v74
	v_or_b32_e32 v2, v2, v6
	v_add3_u32 v7, 16, v10, v7
	v_or_b32_e32 v4, v4, v6
	v_lshl_add_u64 v[68:69], s[60:61], 0, v[2:3]
	v_mov_b32_e32 v2, 0
	v_add_u32_e32 v86, v7, v9
	v_add_u32_e32 v88, v7, v8
	v_lshl_add_u64 v[66:67], s[46:47], 0, v[4:5]
	s_mov_b64 s[2:3], 0
	v_mov_b32_e32 v3, v2
	v_mov_b32_e32 v4, v2
	v_mov_b32_e32 v5, v2
	v_mov_b32_e32 v6, v2
	v_mov_b32_e32 v7, v2
	v_mov_b32_e32 v8, v2
	v_mov_b32_e32 v9, v2
	v_mov_b32_e32 v10, v2
	v_mov_b32_e32 v11, v2
	v_mov_b32_e32 v12, v2
	v_mov_b32_e32 v13, v2
	v_mov_b32_e32 v14, v2
	v_mov_b32_e32 v15, v2
	v_mov_b32_e32 v16, v2
	v_mov_b32_e32 v17, v2
	s_waitcnt vmcnt(0)
	v_mov_b32_e32 v18, v2
	v_mov_b32_e32 v19, v2
	v_mov_b32_e32 v20, v2
	v_mov_b32_e32 v21, v2
	v_mov_b32_e32 v22, v2
	v_mov_b32_e32 v23, v2
	v_mov_b32_e32 v24, v2
	v_mov_b32_e32 v25, v2
	v_mov_b32_e32 v26, v2
	v_mov_b32_e32 v27, v2
	v_mov_b32_e32 v28, v2
	v_mov_b32_e32 v29, v2
	v_mov_b32_e32 v30, v2
	v_mov_b32_e32 v31, v2
	v_mov_b32_e32 v32, v2
	v_mov_b32_e32 v33, v2
	v_mov_b32_e32 v34, v2
	v_mov_b32_e32 v35, v2
	v_mov_b32_e32 v36, v2
	v_mov_b32_e32 v37, v2
	v_mov_b32_e32 v38, v2
	v_mov_b32_e32 v39, v2
	v_mov_b32_e32 v40, v2
	v_mov_b32_e32 v41, v2
	v_mov_b32_e32 v42, v2
	v_mov_b32_e32 v43, v2
	v_mov_b32_e32 v44, v2
	v_mov_b32_e32 v45, v2
	v_mov_b32_e32 v46, v2
	v_mov_b32_e32 v47, v2
	v_mov_b32_e32 v48, v2
	v_mov_b32_e32 v49, v2
	v_mov_b32_e32 v50, v2
	v_mov_b32_e32 v51, v2
	v_mov_b32_e32 v52, v2
	v_mov_b32_e32 v53, v2
	v_mov_b32_e32 v54, v2
	v_mov_b32_e32 v55, v2
	v_mov_b32_e32 v56, v2
	v_mov_b32_e32 v57, v2
	v_mov_b32_e32 v58, v2
	v_mov_b32_e32 v59, v2
	v_mov_b32_e32 v60, v2
	v_mov_b32_e32 v61, v2
	v_mov_b32_e32 v62, v2
	v_mov_b32_e32 v63, v2
	v_mov_b32_e32 v64, v2
	v_mov_b32_e32 v65, v2
	s_waitcnt vmcnt(0) lgkmcnt(0)
	s_barrier
; #define G_MMA(ks_) __builtin_amdgcn_s_setprio(1); _Pragma("unroll") for (int m = 0; m < 4; ++m) \
;         _Pragma("unroll") for (int n = 0; n < 4; ++n) acc[m][n] = __builtin_amdgcn_mfma_f32_16x16x32_bf16(bfv##ks_[n], af##ks_[m], acc[m][n], 0, 0, 0); __builtin_amdgcn_s_setprio(0);
; template <class Epi>
; DEV void gemm_tile(const bf16_t* __restrict__ A, int lda, const bf16_t* __restrict__ Bt, int ldb, int K, int tm, int tn, char* smem, const Epi& epi) {
;     ...
;     const int nk = K >> 6;
;     G_DMA(0, 0);
;     asm volatile("s_waitcnt vmcnt(0)" ::: "memory");
;     __syncthreads();
; #pragma unroll 4
;     for (int kt = 0; kt < nk; ++kt) {
;         const int cur = kt & 1;
;         if (kt + 1 < nk) G_DMA(cur ^ 1, kt + 1);
;         {
;             G_FRAGS(cur, 0)
;             G_MMA(0)
;             G_FRAGS(cur, 1)
;             G_MMA(1)
;         }
;         asm volatile("s_waitcnt vmcnt(0)" ::: "memory");
;         __syncthreads();
	v_writelane_b32 v255, s88, 24
	v_writelane_b32 v255, s89, 25
	v_writelane_b32 v255, s90, 26
	v_writelane_b32 v255, s91, 27
	v_writelane_b32 v255, s92, 28
	v_writelane_b32 v255, s93, 29
	v_writelane_b32 v255, s94, 30
	v_writelane_b32 v255, s95, 31
	v_readfirstlane_b32 s88, v68
	v_readfirstlane_b32 s89, v69
	v_readfirstlane_b32 s90, v66
	v_readfirstlane_b32 s91, v67
	v_lshl_add_u32 v161, v163, 4, 16
	s_and_b32 s88, s88, 0xffffff80
	s_and_b32 s90, s90, 0xffffff80
	v_readfirstlane_b32 s93, v161
	v_subrev_u32_e32 v89, s88, v68
	v_subrev_u32_e32 v153, s90, v66
	v_add_u32_e32 v150, 0x10000, v89
	v_add_u32_e32 v154, 0x10000, v153
	v_add_u32_e32 v151, 0x20000, v89
	v_add_u32_e32 v155, 0x20000, v153
	v_add_u32_e32 v152, 0x30000, v89
	v_add_u32_e32 v156, 0x30000, v153
	s_add_u32 s94, s93, 0x4000
	s_add_u32 s88, s88, 0x8688080
	s_addc_u32 s89, s89, 0
	s_add_u32 s90, s90, 0x2b68080
	s_addc_u32 s91, s91, 0
	v_and_b32_e32 v161, 15, v163
	v_lshlrev_b32_e32 v161, 7, v161
	v_bfe_u32 v164, v163, 4, 2
	v_and_b32_e32 v165, 7, v163
	v_xor_b32_e32 v164, v164, v165
	v_lshlrev_b32_e32 v165, 4, v164
	v_xor_b32_e32 v164, 4, v164
	v_lshlrev_b32_e32 v164, 4, v164
	v_lshrrev_b32_e32 v157, 7, v163
	v_lshl_add_u32 v157, v157, 13, v161
	v_add_u32_e32 v157, 16, v157
	v_bfe_u32 v159, v163, 6, 1
	v_lshl_add_u32 v159, v159, 13, v161
	v_add_u32_e32 v159, 16, v159
	v_add_u32_e32 v158, v157, v164
	v_add_u32_e32 v160, v159, v164
	v_add_u32_e32 v157, v157, v165
	v_add_u32_e32 v159, v159, v165
	s_mov_b32 m0, s94
	s_nop 0
	global_load_lds_dwordx4 v89, s[88:89]
	s_add_u32 m0, m0, 0x1000
	s_nop 0
	global_load_lds_dwordx4 v150, s[88:89]
	s_add_u32 m0, m0, 0x1000
	s_nop 0
	global_load_lds_dwordx4 v151, s[88:89]
	s_add_u32 m0, m0, 0x1000
	s_nop 0
	global_load_lds_dwordx4 v152, s[88:89]
	s_add_u32 m0, m0, 0x5000
	s_nop 0
	global_load_lds_dwordx4 v153, s[90:91]
	s_add_u32 m0, m0, 0x1000
	s_nop 0
	global_load_lds_dwordx4 v154, s[90:91]
	s_add_u32 m0, m0, 0x1000
	s_nop 0
	global_load_lds_dwordx4 v155, s[90:91]
	s_add_u32 m0, m0, 0x1000
	s_nop 0
	global_load_lds_dwordx4 v156, s[90:91]
	s_add_u32 s88, s88, 0x80
	s_addc_u32 s89, s89, 0
	s_add_u32 s90, s90, 0x80
	s_addc_u32 s91, s91, 0
	ds_read_b128 v[70:73], v157
	ds_read_b128 v[90:93], v157 offset:2048
	ds_read_b128 v[94:97], v157 offset:4096
	ds_read_b128 v[98:101], v157 offset:6144
	ds_read_b128 v[102:105], v159 offset:32768
	ds_read_b128 v[106:109], v159 offset:34816
	ds_read_b128 v[110:113], v159 offset:36864
	ds_read_b128 v[114:117], v159 offset:38912
	v_readlane_b32 s95, v251, 0
	s_nop 0
	s_cmp_lt_u32 s95, 0x100
	s_cbranch_scc1 .Lgemm_up_lowprio
	s_setprio 1
.Lgemm_up_lowprio:
	s_movk_i32 s92, 7
.Lgemm_up_loop:
	ds_read_b128 v[118:121], v158
	ds_read_b128 v[122:125], v158 offset:2048
	ds_read_b128 v[126:129], v158 offset:4096
	ds_read_b128 v[130:133], v158 offset:6144
	ds_read_b128 v[134:137], v160 offset:32768
	ds_read_b128 v[138:141], v160 offset:34816
	ds_read_b128 v[142:145], v160 offset:36864
	ds_read_b128 v[146:149], v160 offset:38912
	s_waitcnt lgkmcnt(8)
	v_mfma_f32_16x16x32_bf16 v[2:5], v[102:105], v[70:73], v[2:5]
	v_mfma_f32_16x16x32_bf16 v[6:9], v[106:109], v[70:73], v[6:9]
	v_mfma_f32_16x16x32_bf16 v[10:13], v[110:113], v[70:73], v[10:13]
	v_mfma_f32_16x16x32_bf16 v[14:17], v[114:117], v[70:73], v[14:17]
	v_mfma_f32_16x16x32_bf16 v[18:21], v[102:105], v[90:93], v[18:21]
	v_mfma_f32_16x16x32_bf16 v[22:25], v[106:109], v[90:93], v[22:25]
	v_mfma_f32_16x16x32_bf16 v[26:29], v[110:113], v[90:93], v[26:29]
	v_mfma_f32_16x16x32_bf16 v[30:33], v[114:117], v[90:93], v[30:33]
	v_mfma_f32_16x16x32_bf16 v[34:37], v[102:105], v[94:97], v[34:37]
	v_mfma_f32_16x16x32_bf16 v[38:41], v[106:109], v[94:97], v[38:41]
	v_mfma_f32_16x16x32_bf16 v[42:45], v[110:113], v[94:97], v[42:45]
	v_mfma_f32_16x16x32_bf16 v[46:49], v[114:117], v[94:97], v[46:49]
	v_mfma_f32_16x16x32_bf16 v[50:53], v[102:105], v[98:101], v[50:53]
	v_mfma_f32_16x16x32_bf16 v[54:57], v[106:109], v[98:101], v[54:57]
	v_mfma_f32_16x16x32_bf16 v[58:61], v[110:113], v[98:101], v[58:61]
	v_mfma_f32_16x16x32_bf16 v[62:65], v[114:117], v[98:101], v[62:65]
	s_waitcnt vmcnt(0) lgkmcnt(0)
	s_barrier
	ds_read_b128 v[70:73], v157 offset:16384
	ds_read_b128 v[90:93], v157 offset:18432
	ds_read_b128 v[94:97], v157 offset:20480
	ds_read_b128 v[98:101], v157 offset:22528
	ds_read_b128 v[102:105], v159 offset:49152
	ds_read_b128 v[106:109], v159 offset:51200
	ds_read_b128 v[110:113], v159 offset:53248
	ds_read_b128 v[114:117], v159 offset:55296
	s_mov_b32 m0, s93
	v_mfma_f32_16x16x32_bf16 v[2:5], v[134:137], v[118:121], v[2:5]
	global_load_lds_dwordx4 v89, s[88:89]
	s_add_u32 m0, m0, 0x1000
	v_mfma_f32_16x16x32_bf16 v[6:9], v[138:141], v[118:121], v[6:9]
	global_load_lds_dwordx4 v150, s[88:89]
	s_add_u32 m0, m0, 0x1000
	v_mfma_f32_16x16x32_bf16 v[10:13], v[142:145], v[118:121], v[10:13]
	global_load_lds_dwordx4 v151, s[88:89]
	s_add_u32 m0, m0, 0x1000
	v_mfma_f32_16x16x32_bf16 v[14:17], v[146:149], v[118:121], v[14:17]
	global_load_lds_dwordx4 v152, s[88:89]
	s_add_u32 m0, m0, 0x5000
	v_mfma_f32_16x16x32_bf16 v[18:21], v[134:137], v[122:125], v[18:21]
	global_load_lds_dwordx4 v153, s[90:91]
	s_add_u32 m0, m0, 0x1000
	v_mfma_f32_16x16x32_bf16 v[22:25], v[138:141], v[122:125], v[22:25]
	global_load_lds_dwordx4 v154, s[90:91]
	s_add_u32 m0, m0, 0x1000
	v_mfma_f32_16x16x32_bf16 v[26:29], v[142:145], v[122:125], v[26:29]
	global_load_lds_dwordx4 v155, s[90:91]
	s_add_u32 m0, m0, 0x1000
	v_mfma_f32_16x16x32_bf16 v[30:33], v[146:149], v[122:125], v[30:33]
	global_load_lds_dwordx4 v156, s[90:91]
	v_mfma_f32_16x16x32_bf16 v[34:37], v[134:137], v[126:129], v[34:37]
	s_add_u32 s88, s88, 0x80
	v_mfma_f32_16x16x32_bf16 v[38:41], v[138:141], v[126:129], v[38:41]
	s_addc_u32 s89, s89, 0
	v_mfma_f32_16x16x32_bf16 v[42:45], v[142:145], v[126:129], v[42:45]
	s_add_u32 s90, s90, 0x80
	v_mfma_f32_16x16x32_bf16 v[46:49], v[146:149], v[126:129], v[46:49]
	s_addc_u32 s91, s91, 0
	v_mfma_f32_16x16x32_bf16 v[50:53], v[134:137], v[130:133], v[50:53]
	v_mfma_f32_16x16x32_bf16 v[54:57], v[138:141], v[130:133], v[54:57]
	v_mfma_f32_16x16x32_bf16 v[58:61], v[142:145], v[130:133], v[58:61]
	v_mfma_f32_16x16x32_bf16 v[62:65], v[146:149], v[130:133], v[62:65]
	ds_read_b128 v[118:121], v158 offset:16384
	ds_read_b128 v[122:125], v158 offset:18432
	ds_read_b128 v[126:129], v158 offset:20480
	ds_read_b128 v[130:133], v158 offset:22528
	ds_read_b128 v[134:137], v160 offset:49152
	ds_read_b128 v[138:141], v160 offset:51200
	ds_read_b128 v[142:145], v160 offset:53248
	ds_read_b128 v[146:149], v160 offset:55296
	s_waitcnt lgkmcnt(8)
; #define G_MMA(ks_) __builtin_amdgcn_s_setprio(1); _Pragma("unroll") for (int m = 0; m < 4; ++m) \
;         _Pragma("unroll") for (int n = 0; n < 4; ++n) acc[m][n] = __builtin_amdgcn_mfma_f32_16x16x32_bf16(bfv##ks_[n], af##ks_[m], acc[m][n], 0, 0, 0); __builtin_amdgcn_s_setprio(0);
; template <class Epi>
; DEV void gemm_tile(const bf16_t* __restrict__ A, int lda, const bf16_t* __restrict__ Bt, int ldb, int K, int tm, int tn, char* smem, const Epi& epi) {
;     ...
;     const int nk = K >> 6;
;     G_DMA(0, 0);
;     asm volatile("s_waitcnt vmcnt(0)" ::: "memory");
;     __syncthreads();
; #pragma unroll 4
;     for (int kt = 0; kt < nk; ++kt) {
;         const int cur = kt & 1;
;         if (kt + 1 < nk) G_DMA(cur ^ 1, kt + 1);
;         {
;             G_FRAGS(cur, 0)
;             G_MMA(0)
;             G_FRAGS(cur, 1)
;             G_MMA(1)
;         }
;         asm volatile("s_waitcnt vmcnt(0)" ::: "memory");
;         __syncthreads();
	v_mfma_f32_16x16x32_bf16 v[2:5], v[102:105], v[70:73], v[2:5]
	v_mfma_f32_16x16x32_bf16 v[6:9], v[106:109], v[70:73], v[6:9]
	v_mfma_f32_16x16x32_bf16 v[10:13], v[110:113], v[70:73], v[10:13]
	v_mfma_f32_16x16x32_bf16 v[14:17], v[114:117], v[70:73], v[14:17]
	v_mfma_f32_16x16x32_bf16 v[18:21], v[102:105], v[90:93], v[18:21]
	v_mfma_f32_16x16x32_bf16 v[22:25], v[106:109], v[90:93], v[22:25]
	v_mfma_f32_16x16x32_bf16 v[26:29], v[110:113], v[90:93], v[26:29]
	v_mfma_f32_16x16x32_bf16 v[30:33], v[114:117], v[90:93], v[30:33]
	v_mfma_f32_16x16x32_bf16 v[34:37], v[102:105], v[94:97], v[34:37]
	v_mfma_f32_16x16x32_bf16 v[38:41], v[106:109], v[94:97], v[38:41]
	v_mfma_f32_16x16x32_bf16 v[42:45], v[110:113], v[94:97], v[42:45]
	v_mfma_f32_16x16x32_bf16 v[46:49], v[114:117], v[94:97], v[46:49]
	v_mfma_f32_16x16x32_bf16 v[50:53], v[102:105], v[98:101], v[50:53]
	v_mfma_f32_16x16x32_bf16 v[54:57], v[106:109], v[98:101], v[54:57]
	v_mfma_f32_16x16x32_bf16 v[58:61], v[110:113], v[98:101], v[58:61]
	v_mfma_f32_16x16x32_bf16 v[62:65], v[114:117], v[98:101], v[62:65]
	s_waitcnt vmcnt(0) lgkmcnt(0)
	s_barrier
	ds_read_b128 v[70:73], v157
	ds_read_b128 v[90:93], v157 offset:2048
	ds_read_b128 v[94:97], v157 offset:4096
	ds_read_b128 v[98:101], v157 offset:6144
	ds_read_b128 v[102:105], v159 offset:32768
	ds_read_b128 v[106:109], v159 offset:34816
	ds_read_b128 v[110:113], v159 offset:36864
	ds_read_b128 v[114:117], v159 offset:38912
	s_mov_b32 m0, s94
	v_mfma_f32_16x16x32_bf16 v[2:5], v[134:137], v[118:121], v[2:5]
	global_load_lds_dwordx4 v89, s[88:89]
	s_add_u32 m0, m0, 0x1000
	v_mfma_f32_16x16x32_bf16 v[6:9], v[138:141], v[118:121], v[6:9]
	global_load_lds_dwordx4 v150, s[88:89]
	s_add_u32 m0, m0, 0x1000
	v_mfma_f32_16x16x32_bf16 v[10:13], v[142:145], v[118:121], v[10:13]
	global_load_lds_dwordx4 v151, s[88:89]
	s_add_u32 m0, m0, 0x1000
	v_mfma_f32_16x16x32_bf16 v[14:17], v[146:149], v[118:121], v[14:17]
	global_load_lds_dwordx4 v152, s[88:89]
	s_add_u32 m0, m0, 0x5000
	v_mfma_f32_16x16x32_bf16 v[18:21], v[134:137], v[122:125], v[18:21]
	global_load_lds_dwordx4 v153, s[90:91]
	s_add_u32 m0, m0, 0x1000
	v_mfma_f32_16x16x32_bf16 v[22:25], v[138:141], v[122:125], v[22:25]
	global_load_lds_dwordx4 v154, s[90:91]
	s_add_u32 m0, m0, 0x1000
	v_mfma_f32_16x16x32_bf16 v[26:29], v[142:145], v[122:125], v[26:29]
	global_load_lds_dwordx4 v155, s[90:91]
	s_add_u32 m0, m0, 0x1000
	v_mfma_f32_16x16x32_bf16 v[30:33], v[146:149], v[122:125], v[30:33]
	global_load_lds_dwordx4 v156, s[90:91]
	v_mfma_f32_16x16x32_bf16 v[34:37], v[134:137], v[126:129], v[34:37]
	s_add_u32 s88, s88, 0x80
	v_mfma_f32_16x16x32_bf16 v[38:41], v[138:141], v[126:129], v[38:41]
	s_addc_u32 s89, s89, 0
	v_mfma_f32_16x16x32_bf16 v[42:45], v[142:145], v[126:129], v[42:45]
	s_add_u32 s90, s90, 0x80
	v_mfma_f32_16x16x32_bf16 v[46:49], v[146:149], v[126:129], v[46:49]
	s_addc_u32 s91, s91, 0
	v_mfma_f32_16x16x32_bf16 v[50:53], v[134:137], v[130:133], v[50:53]
	v_mfma_f32_16x16x32_bf16 v[54:57], v[138:141], v[130:133], v[54:57]
	v_mfma_f32_16x16x32_bf16 v[58:61], v[142:145], v[130:133], v[58:61]
	v_mfma_f32_16x16x32_bf16 v[62:65], v[146:149], v[130:133], v[62:65]
	s_sub_u32 s92, s92, 1
	s_cmp_lg_u32 s92, 0
	s_cbranch_scc1 .Lgemm_up_loop
	ds_read_b128 v[118:121], v158
	ds_read_b128 v[122:125], v158 offset:2048
	ds_read_b128 v[126:129], v158 offset:4096
	ds_read_b128 v[130:133], v158 offset:6144
	ds_read_b128 v[134:137], v160 offset:32768
	ds_read_b128 v[138:141], v160 offset:34816
	ds_read_b128 v[142:145], v160 offset:36864
	ds_read_b128 v[146:149], v160 offset:38912
	s_waitcnt lgkmcnt(8)
	v_mfma_f32_16x16x32_bf16 v[2:5], v[102:105], v[70:73], v[2:5]
	v_mfma_f32_16x16x32_bf16 v[6:9], v[106:109], v[70:73], v[6:9]
	v_mfma_f32_16x16x32_bf16 v[10:13], v[110:113], v[70:73], v[10:13]
	v_mfma_f32_16x16x32_bf16 v[14:17], v[114:117], v[70:73], v[14:17]
	v_mfma_f32_16x16x32_bf16 v[18:21], v[102:105], v[90:93], v[18:21]
	v_mfma_f32_16x16x32_bf16 v[22:25], v[106:109], v[90:93], v[22:25]
	v_mfma_f32_16x16x32_bf16 v[26:29], v[110:113], v[90:93], v[26:29]
	v_mfma_f32_16x16x32_bf16 v[30:33], v[114:117], v[90:93], v[30:33]
	v_mfma_f32_16x16x32_bf16 v[34:37], v[102:105], v[94:97], v[34:37]
	v_mfma_f32_16x16x32_bf16 v[38:41], v[106:109], v[94:97], v[38:41]
	v_mfma_f32_16x16x32_bf16 v[42:45], v[110:113], v[94:97], v[42:45]
	v_mfma_f32_16x16x32_bf16 v[46:49], v[114:117], v[94:97], v[46:49]
	v_mfma_f32_16x16x32_bf16 v[50:53], v[102:105], v[98:101], v[50:53]
	v_mfma_f32_16x16x32_bf16 v[54:57], v[106:109], v[98:101], v[54:57]
	v_mfma_f32_16x16x32_bf16 v[58:61], v[110:113], v[98:101], v[58:61]
	v_mfma_f32_16x16x32_bf16 v[62:65], v[114:117], v[98:101], v[62:65]
	s_waitcnt vmcnt(0) lgkmcnt(0)
	s_barrier
; #define G_MMA(ks_) __builtin_amdgcn_s_setprio(1); _Pragma("unroll") for (int m = 0; m < 4; ++m) \
;         _Pragma("unroll") for (int n = 0; n < 4; ++n) acc[m][n] = __builtin_amdgcn_mfma_f32_16x16x32_bf16(bfv##ks_[n], af##ks_[m], acc[m][n], 0, 0, 0); __builtin_amdgcn_s_setprio(0);
; template <class Epi>
; DEV void gemm_tile(const bf16_t* __restrict__ A, int lda, const bf16_t* __restrict__ Bt, int ldb, int K, int tm, int tn, char* smem, const Epi& epi) {
;     ...
;     const int nk = K >> 6;
;     G_DMA(0, 0);
;     asm volatile("s_waitcnt vmcnt(0)" ::: "memory");
;     __syncthreads();
; #pragma unroll 4
;     for (int kt = 0; kt < nk; ++kt) {
;         const int cur = kt & 1;
;         if (kt + 1 < nk) G_DMA(cur ^ 1, kt + 1);
;         {
;             G_FRAGS(cur, 0)
;             G_MMA(0)
;             G_FRAGS(cur, 1)
;             G_MMA(1)
;         }
;         asm volatile("s_waitcnt vmcnt(0)" ::: "memory");
;         __syncthreads();
;     }
	ds_read_b128 v[70:73], v157 offset:16384
	ds_read_b128 v[90:93], v157 offset:18432
	ds_read_b128 v[94:97], v157 offset:20480
	ds_read_b128 v[98:101], v157 offset:22528
	ds_read_b128 v[102:105], v159 offset:49152
	ds_read_b128 v[106:109], v159 offset:51200
	ds_read_b128 v[110:113], v159 offset:53248
	ds_read_b128 v[114:117], v159 offset:55296
	v_mfma_f32_16x16x32_bf16 v[2:5], v[134:137], v[118:121], v[2:5]
	v_mfma_f32_16x16x32_bf16 v[6:9], v[138:141], v[118:121], v[6:9]
	v_mfma_f32_16x16x32_bf16 v[10:13], v[142:145], v[118:121], v[10:13]
	v_mfma_f32_16x16x32_bf16 v[14:17], v[146:149], v[118:121], v[14:17]
	v_mfma_f32_16x16x32_bf16 v[18:21], v[134:137], v[122:125], v[18:21]
	v_mfma_f32_16x16x32_bf16 v[22:25], v[138:141], v[122:125], v[22:25]
	v_mfma_f32_16x16x32_bf16 v[26:29], v[142:145], v[122:125], v[26:29]
	v_mfma_f32_16x16x32_bf16 v[30:33], v[146:149], v[122:125], v[30:33]
	v_mfma_f32_16x16x32_bf16 v[34:37], v[134:137], v[126:129], v[34:37]
	v_mfma_f32_16x16x32_bf16 v[38:41], v[138:141], v[126:129], v[38:41]
	v_mfma_f32_16x16x32_bf16 v[42:45], v[142:145], v[126:129], v[42:45]
	v_mfma_f32_16x16x32_bf16 v[46:49], v[146:149], v[126:129], v[46:49]
	v_mfma_f32_16x16x32_bf16 v[50:53], v[134:137], v[130:133], v[50:53]
	v_mfma_f32_16x16x32_bf16 v[54:57], v[138:141], v[130:133], v[54:57]
	v_mfma_f32_16x16x32_bf16 v[58:61], v[142:145], v[130:133], v[58:61]
	v_mfma_f32_16x16x32_bf16 v[62:65], v[146:149], v[130:133], v[62:65]
	ds_read_b128 v[118:121], v158 offset:16384
	ds_read_b128 v[122:125], v158 offset:18432
	ds_read_b128 v[126:129], v158 offset:20480
	ds_read_b128 v[130:133], v158 offset:22528
	ds_read_b128 v[134:137], v160 offset:49152
	ds_read_b128 v[138:141], v160 offset:51200
	ds_read_b128 v[142:145], v160 offset:53248
	ds_read_b128 v[146:149], v160 offset:55296
	s_waitcnt lgkmcnt(8)
	v_mfma_f32_16x16x32_bf16 v[2:5], v[102:105], v[70:73], v[2:5]
	v_mfma_f32_16x16x32_bf16 v[6:9], v[106:109], v[70:73], v[6:9]
	v_mfma_f32_16x16x32_bf16 v[10:13], v[110:113], v[70:73], v[10:13]
	v_mfma_f32_16x16x32_bf16 v[14:17], v[114:117], v[70:73], v[14:17]
	v_mfma_f32_16x16x32_bf16 v[18:21], v[102:105], v[90:93], v[18:21]
	v_mfma_f32_16x16x32_bf16 v[22:25], v[106:109], v[90:93], v[22:25]
	v_mfma_f32_16x16x32_bf16 v[26:29], v[110:113], v[90:93], v[26:29]
	v_mfma_f32_16x16x32_bf16 v[30:33], v[114:117], v[90:93], v[30:33]
	v_mfma_f32_16x16x32_bf16 v[34:37], v[102:105], v[94:97], v[34:37]
	v_mfma_f32_16x16x32_bf16 v[38:41], v[106:109], v[94:97], v[38:41]
	v_mfma_f32_16x16x32_bf16 v[42:45], v[110:113], v[94:97], v[42:45]
	v_mfma_f32_16x16x32_bf16 v[46:49], v[114:117], v[94:97], v[46:49]
	v_mfma_f32_16x16x32_bf16 v[50:53], v[102:105], v[98:101], v[50:53]
	v_mfma_f32_16x16x32_bf16 v[54:57], v[106:109], v[98:101], v[54:57]
	v_mfma_f32_16x16x32_bf16 v[58:61], v[110:113], v[98:101], v[58:61]
	v_mfma_f32_16x16x32_bf16 v[62:65], v[114:117], v[98:101], v[62:65]
	s_waitcnt lgkmcnt(0)
	s_barrier
	v_mfma_f32_16x16x32_bf16 v[2:5], v[134:137], v[118:121], v[2:5]
	v_mfma_f32_16x16x32_bf16 v[6:9], v[138:141], v[118:121], v[6:9]
	v_mfma_f32_16x16x32_bf16 v[10:13], v[142:145], v[118:121], v[10:13]
	v_mfma_f32_16x16x32_bf16 v[14:17], v[146:149], v[118:121], v[14:17]
	v_mfma_f32_16x16x32_bf16 v[18:21], v[134:137], v[122:125], v[18:21]
	v_mfma_f32_16x16x32_bf16 v[22:25], v[138:141], v[122:125], v[22:25]
	v_mfma_f32_16x16x32_bf16 v[26:29], v[142:145], v[122:125], v[26:29]
	v_mfma_f32_16x16x32_bf16 v[30:33], v[146:149], v[122:125], v[30:33]
	v_mfma_f32_16x16x32_bf16 v[34:37], v[134:137], v[126:129], v[34:37]
	v_mfma_f32_16x16x32_bf16 v[38:41], v[138:141], v[126:129], v[38:41]
	v_mfma_f32_16x16x32_bf16 v[42:45], v[142:145], v[126:129], v[42:45]
	v_mfma_f32_16x16x32_bf16 v[46:49], v[146:149], v[126:129], v[46:49]
	v_mfma_f32_16x16x32_bf16 v[50:53], v[134:137], v[130:133], v[50:53]
	v_mfma_f32_16x16x32_bf16 v[54:57], v[138:141], v[130:133], v[54:57]
	v_mfma_f32_16x16x32_bf16 v[58:61], v[142:145], v[130:133], v[58:61]
	v_mfma_f32_16x16x32_bf16 v[62:65], v[146:149], v[130:133], v[62:65]
	s_setprio 0
	v_readlane_b32 s88, v255, 24
	v_readlane_b32 s89, v255, 25
	v_readlane_b32 s90, v255, 26
	v_readlane_b32 s91, v255, 27
	v_readlane_b32 s92, v255, 28
	v_readlane_b32 s93, v255, 29
	v_readlane_b32 s94, v255, 30
	v_readlane_b32 s95, v255, 31
	s_nop 7
	s_nop 1

; template <class Epi>
; DEV void gemm_tile(const bf16_t* __restrict__ A, int lda, const bf16_t* __restrict__ Bt, int ldb, int K, int tm, int tn, char* smem, const Epi& epi) {
;     ...
;     const int lrow = tid >> 3, lcc = (tid & 7) * 8, lsw = (((tid & 7) ^ (lrow & 7)) * 8);
;     const bf16_t* Ag = A + (size_t)(tm * 128 + lrow) * lda + lcc;
;     const bf16_t* Bg = Bt + (size_t)(tn * 128 + lrow) * ldb + lcc;
;     f32x4 acc[4][4];
; #pragma unroll
;     for (int m = 0; m < 4; ++m)
; #pragma unroll
;         for (int n = 0; n < 4; ++n) acc[m][n] = (f32x4){0.f, 0.f, 0.f, 0.f};
;     const int gsw = (((tid & 7) ^ (lrow & 7)) * 8);
;     const bf16_t* Ad = A + (size_t)(tm * 128 + lrow) * lda + gsw;
;     const bf16_t* Bd = Bt + (size_t)(tn * 128 + lrow) * ldb + gsw;
;     char* Asb = (char*)As; char* Bsb = (char*)Bs;
;     ...
;     const int nk = K >> 6;
;     G_DMA(0, 0);
;     asm volatile("s_waitcnt vmcnt(0)" ::: "memory");
;     __syncthreads();
; template <class Epi>
; DEV void gemm_phase(const bf16_t* A, int lda, const bf16_t* Bt, int ldb, int K, int ntm, int ntn, bool skip_ctx, char* smem, const Epi& epi) {
;     ...
;         for (int q = slot; q < per; q += nper) {
;             int tm, tn;
;             if (q < fullq) { const int tb = q / (R * 8), r = q - tb * (R * 8); tm = r >> 3; tn = tb * 8 + (r & 7); }
;             else { const int q2 = q - fullq; tm = q2 / w; tn = nfb * 8 + (q2 - tm * w); }
;             tm += xcd * R;
;             if (skip_ctx && ((tm * 128) % TT) >= SEQ) continue;
;             gemm_tile(A, lda, Bt, ldb, K, tm, tn, smem, epi);
.LBB0_162:
	s_lshr_b32 s43, s37, 3
	v_readlane_b32 s42, v253, 31
	s_add_i32 s43, s43, s42
	s_lshl_b32 s42, s43, 7
	s_mul_hi_u32 s44, s42, 0x38e38e39
	s_lshr_b32 s44, s44, 9
	s_mulk_i32 s44, 0x900
	s_sub_i32 s44, s42, s44
	s_cmpk_gt_u32 s44, 0x7ff
	s_cselect_b64 s[44:45], -1, 0
	s_and_b64 s[44:45], s[54:55], s[44:45]
	s_and_b64 vcc, exec, s[44:45]
	s_cbranch_vccnz .LBB0_161
	v_mov_b32_e32 v10, v163
	s_and_b32 s44, s36, 0x380
	s_waitcnt vmcnt(10)
	v_ashrrev_i32_e32 v0, 3, v10
	v_add_u32_e32 v2, s42, v0
	v_ashrrev_i32_e32 v3, 31, v2
	v_add_u32_e32 v4, s44, v0
	v_xor_b32_e32 v0, v0, v10
	v_ashrrev_i32_e32 v5, 31, v4
	v_lshlrev_b64 v[2:3], 11, v[2:3]
	v_lshlrev_b32_e32 v0, 4, v0
	s_waitcnt vmcnt(5)
	v_lshl_add_u32 v22, v10, 4, 16
	v_lshl_add_u64 v[2:3], s[26:27], 0, v[2:3]
	v_lshlrev_b64 v[4:5], 11, v[4:5]
	v_and_b32_e32 v0, 0x70, v0
	s_waitcnt vmcnt(4)
	v_add_u32_e32 v21, 0x8000, v22
	v_readfirstlane_b32 s65, v22
	v_lshl_add_u64 v[8:9], s[38:39], 0, v[4:5]
	v_lshl_add_u64 v[4:5], v[2:3], 0, v[0:1]
	s_mov_b32 m0, s65
	v_readfirstlane_b32 s53, v21
	v_add_u32_e32 v23, 0x1000, v22
	v_lshl_add_u64 v[2:3], v[8:9], 0, v[0:1]
	global_load_lds_dwordx4 v[4:5], off
	s_mov_b32 m0, s53
	s_mov_b64 s[90:91], 0x10000
	v_readfirstlane_b32 s62, v23
	v_add_u32_e32 v24, 0x9000, v22
	global_load_lds_dwordx4 v[2:3], off
	v_lshl_add_u64 v[8:9], v[4:5], 0, s[90:91]
	s_mov_b32 m0, s62
	v_readfirstlane_b32 s63, v24
	v_add_u32_e32 v25, 0x2000, v22
	global_load_lds_dwordx4 v[8:9], off
	v_lshl_add_u64 v[8:9], v[2:3], 0, s[90:91]
	s_mov_b32 m0, s63
	s_mov_b64 s[92:93], 0x20000
	v_readfirstlane_b32 s64, v25
	v_add_u32_e32 v26, 0xa000, v22
	global_load_lds_dwordx4 v[8:9], off
	v_lshl_add_u64 v[8:9], v[4:5], 0, s[92:93]
	s_mov_b32 m0, s64
	v_readfirstlane_b32 s84, v26
	v_add_u32_e32 v27, 0x3000, v22
	global_load_lds_dwordx4 v[8:9], off
	v_lshl_add_u64 v[8:9], v[2:3], 0, s[92:93]
	s_mov_b32 m0, s84
	s_mov_b64 s[0:1], 0x30000
	v_readfirstlane_b32 s85, v27
	v_add_u32_e32 v28, 0xb000, v22
	global_load_lds_dwordx4 v[8:9], off
	v_lshl_add_u64 v[8:9], v[4:5], 0, s[0:1]
	s_mov_b32 m0, s85
	v_readfirstlane_b32 s86, v28
	global_load_lds_dwordx4 v[8:9], off
	v_lshl_add_u64 v[8:9], v[2:3], 0, s[0:1]
	s_mov_b32 m0, s86
	v_and_b32_e32 v7, 15, v10
	global_load_lds_dwordx4 v[8:9], off
	v_ashrrev_i32_e32 v8, 7, v10
	v_lshlrev_b32_e32 v9, 13, v8
	v_lshlrev_b32_e32 v12, 7, v7
	v_bfe_u32 v6, v10, 6, 1
	v_lshrrev_b32_e32 v11, 4, v10
	v_add3_u32 v29, 16, v9, v12
	v_and_b32_e32 v9, 7, v10
	v_bfe_u32 v0, v10, 4, 2
	v_bitop3_b32 v10, v11, v9, 3 bitop3:0x6c
	v_lshlrev_b32_e32 v11, 13, v6
	v_add3_u32 v110, 16, v11, v12
	v_add_u32_e32 v11, 0x4000, v22
	s_mov_b64 s[46:47], 0x80
	v_add_u32_e32 v12, 0xc000, v22
	v_readfirstlane_b32 s49, v11
	v_lshl_add_u64 v[14:15], v[4:5], 0, s[46:47]
	s_mov_b32 m0, s49
	v_readfirstlane_b32 s45, v12
	v_add_u32_e32 v13, 0x5000, v22
	s_waitcnt vmcnt(0)
	s_waitcnt vmcnt(0) lgkmcnt(0)
	s_barrier
	v_writelane_b32 v255, s88, 24
	v_writelane_b32 v255, s89, 25
	v_writelane_b32 v255, s90, 26
	v_writelane_b32 v255, s91, 27
	v_writelane_b32 v255, s92, 28
	v_writelane_b32 v255, s93, 29
	v_writelane_b32 v255, s94, 30
	v_writelane_b32 v255, s95, 31
	v_readfirstlane_b32 s88, v4
	v_readfirstlane_b32 s89, v5
	v_readfirstlane_b32 s90, v2
	v_readfirstlane_b32 s91, v3
	v_lshl_add_u32 v225, v163, 4, 16
	s_and_b32 s88, s88, 0xffffff80
	s_and_b32 s90, s90, 0xffffff80
	v_readfirstlane_b32 s93, v225
	v_subrev_u32_e32 v184, s88, v4
	v_subrev_u32_e32 v217, s90, v2
	v_add_u32_e32 v214, 0x10000, v184
	v_add_u32_e32 v218, 0x10000, v217
	v_add_u32_e32 v215, 0x20000, v184
	v_add_u32_e32 v219, 0x20000, v217
	v_add_u32_e32 v216, 0x30000, v184
	v_add_u32_e32 v220, 0x30000, v217
	s_add_u32 s94, s93, 0x4000
	s_add_u32 s88, s88, 0x80
	s_addc_u32 s89, s89, 0
	s_add_u32 s90, s90, 0x80
	s_addc_u32 s91, s91, 0
	v_and_b32_e32 v225, 15, v163
	v_lshlrev_b32_e32 v225, 7, v225
	v_bfe_u32 v226, v163, 4, 2
	v_and_b32_e32 v227, 7, v163
	v_xor_b32_e32 v226, v226, v227
	v_lshlrev_b32_e32 v227, 4, v226
	v_xor_b32_e32 v226, 4, v226
	v_lshlrev_b32_e32 v226, 4, v226
	v_lshrrev_b32_e32 v221, 7, v163
	v_lshl_add_u32 v221, v221, 13, v225
	v_add_u32_e32 v221, 16, v221
	v_bfe_u32 v223, v163, 6, 1
	v_lshl_add_u32 v223, v223, 13, v225
	v_add_u32_e32 v223, 16, v223
	v_add_u32_e32 v222, v221, v226
	v_add_u32_e32 v224, v223, v226
	v_add_u32_e32 v221, v221, v227
	v_add_u32_e32 v223, v223, v227
	v_mov_b32_e32 v62, 0
	v_mov_b32_e32 v63, 0
	v_mov_b32_e32 v64, 0
	v_mov_b32_e32 v65, 0
	v_mov_b32_e32 v66, 0
	v_mov_b32_e32 v67, 0
	v_mov_b32_e32 v68, 0
	v_mov_b32_e32 v69, 0
	v_mov_b32_e32 v70, 0
	v_mov_b32_e32 v71, 0
	v_mov_b32_e32 v72, 0
	v_mov_b32_e32 v73, 0
	v_mov_b32_e32 v2, 0
	v_mov_b32_e32 v3, 0
	v_mov_b32_e32 v4, 0
	v_mov_b32_e32 v5, 0
	v_mov_b32_e32 v18, 0
	v_mov_b32_e32 v19, 0
	v_mov_b32_e32 v20, 0
	v_mov_b32_e32 v21, 0
	v_mov_b32_e32 v28, 0
	v_mov_b32_e32 v29, 0
	v_mov_b32_e32 v30, 0
	v_mov_b32_e32 v31, 0
	v_mov_b32_e32 v56, 0
	v_mov_b32_e32 v57, 0
	v_mov_b32_e32 v58, 0
	v_mov_b32_e32 v59, 0
	v_mov_b32_e32 v10, 0
	v_mov_b32_e32 v11, 0
	v_mov_b32_e32 v12, 0
	v_mov_b32_e32 v13, 0
	v_mov_b32_e32 v22, 0
	v_mov_b32_e32 v23, 0
	v_mov_b32_e32 v24, 0
	v_mov_b32_e32 v25, 0
	v_mov_b32_e32 v32, 0
	v_mov_b32_e32 v33, 0
	v_mov_b32_e32 v34, 0
	v_mov_b32_e32 v35, 0
	v_mov_b32_e32 v74, 0
	v_mov_b32_e32 v75, 0
	v_mov_b32_e32 v76, 0
	v_mov_b32_e32 v77, 0
	v_mov_b32_e32 v36, 0
	v_mov_b32_e32 v37, 0
	v_mov_b32_e32 v38, 0
	v_mov_b32_e32 v39, 0
	v_mov_b32_e32 v44, 0
	v_mov_b32_e32 v45, 0
	v_mov_b32_e32 v46, 0
	v_mov_b32_e32 v47, 0
	v_mov_b32_e32 v48, 0
	v_mov_b32_e32 v49, 0
	v_mov_b32_e32 v50, 0
	v_mov_b32_e32 v51, 0
	v_mov_b32_e32 v52, 0
	v_mov_b32_e32 v53, 0
	v_mov_b32_e32 v54, 0
	v_mov_b32_e32 v55, 0
	v_mov_b32_e32 v14, 0
	v_mov_b32_e32 v15, 0
	v_mov_b32_e32 v16, 0
	v_mov_b32_e32 v17, 0
	s_mov_b32 m0, s94
	s_nop 0
	global_load_lds_dwordx4 v184, s[88:89]
	s_add_u32 m0, m0, 0x1000
	s_nop 0
	global_load_lds_dwordx4 v214, s[88:89]
	s_add_u32 m0, m0, 0x1000
	s_nop 0
	global_load_lds_dwordx4 v215, s[88:89]
	s_add_u32 m0, m0, 0x1000
	s_nop 0
	global_load_lds_dwordx4 v216, s[88:89]
	s_add_u32 m0, m0, 0x5000
	s_nop 0
	global_load_lds_dwordx4 v217, s[90:91]
	s_add_u32 m0, m0, 0x1000
	s_nop 0
	global_load_lds_dwordx4 v218, s[90:91]
	s_add_u32 m0, m0, 0x1000
	s_nop 0
	global_load_lds_dwordx4 v219, s[90:91]
	s_add_u32 m0, m0, 0x1000
	s_nop 0
	global_load_lds_dwordx4 v220, s[90:91]
	s_add_u32 s88, s88, 0x80
	s_addc_u32 s89, s89, 0
	s_add_u32 s90, s90, 0x80
	s_addc_u32 s91, s91, 0
	ds_read_b128 v[126:129], v221
	ds_read_b128 v[130:133], v221 offset:2048
	ds_read_b128 v[134:137], v221 offset:4096
	ds_read_b128 v[138:141], v221 offset:6144
	ds_read_b128 v[142:145], v223 offset:32768
	ds_read_b128 v[146:149], v223 offset:34816
	ds_read_b128 v[150:153], v223 offset:36864
	ds_read_b128 v[154:157], v223 offset:38912
	v_readlane_b32 s95, v251, 0
	s_nop 0
	s_cmp_lt_u32 s95, 0x100
	s_cbranch_scc1 .Lgemm_out_lowprio
	s_setprio 1

; #define G_MMA(ks_) __builtin_amdgcn_s_setprio(1); _Pragma("unroll") for (int m = 0; m < 4; ++m) \
;         _Pragma("unroll") for (int n = 0; n < 4; ++n) acc[m][n] = __builtin_amdgcn_mfma_f32_16x16x32_bf16(bfv##ks_[n], af##ks_[m], acc[m][n], 0, 0, 0); __builtin_amdgcn_s_setprio(0);
; template <class Epi>
; DEV void gemm_tile(const bf16_t* __restrict__ A, int lda, const bf16_t* __restrict__ Bt, int ldb, int K, int tm, int tn, char* smem, const Epi& epi) {
;     ...
;     const int nk = K >> 6;
;     G_DMA(0, 0);
;     asm volatile("s_waitcnt vmcnt(0)" ::: "memory");
;     __syncthreads();
; #pragma unroll 4
;     for (int kt = 0; kt < nk; ++kt) {
;         const int cur = kt & 1;
;         if (kt + 1 < nk) G_DMA(cur ^ 1, kt + 1);
;         {
;             G_FRAGS(cur, 0)
;             G_MMA(0)
;             G_FRAGS(cur, 1)
;             G_MMA(1)
;         }
;         asm volatile("s_waitcnt vmcnt(0)" ::: "memory");
;         __syncthreads();
;     }
.Lgemm_out_loop:
	ds_read_b128 v[158:161], v222
	ds_read_b128 v[164:167], v222 offset:2048
	ds_read_b128 v[168:171], v222 offset:4096
	ds_read_b128 v[172:175], v222 offset:6144
	ds_read_b128 v[176:179], v224 offset:32768
	ds_read_b128 v[180:183], v224 offset:34816
	ds_read_b128 v[192:195], v224 offset:36864
	ds_read_b128 v[210:213], v224 offset:38912
	s_waitcnt lgkmcnt(8)
	v_mfma_f32_16x16x32_bf16 v[62:65], v[142:145], v[126:129], v[62:65]
	v_mfma_f32_16x16x32_bf16 v[66:69], v[146:149], v[126:129], v[66:69]
	v_mfma_f32_16x16x32_bf16 v[70:73], v[150:153], v[126:129], v[70:73]
	v_mfma_f32_16x16x32_bf16 v[2:5], v[154:157], v[126:129], v[2:5]
	v_mfma_f32_16x16x32_bf16 v[18:21], v[142:145], v[130:133], v[18:21]
	v_mfma_f32_16x16x32_bf16 v[28:31], v[146:149], v[130:133], v[28:31]
	v_mfma_f32_16x16x32_bf16 v[56:59], v[150:153], v[130:133], v[56:59]
	v_mfma_f32_16x16x32_bf16 v[10:13], v[154:157], v[130:133], v[10:13]
	v_mfma_f32_16x16x32_bf16 v[22:25], v[142:145], v[134:137], v[22:25]
	v_mfma_f32_16x16x32_bf16 v[32:35], v[146:149], v[134:137], v[32:35]
	v_mfma_f32_16x16x32_bf16 v[74:77], v[150:153], v[134:137], v[74:77]
	v_mfma_f32_16x16x32_bf16 v[36:39], v[154:157], v[134:137], v[36:39]
	v_mfma_f32_16x16x32_bf16 v[44:47], v[142:145], v[138:141], v[44:47]
	v_mfma_f32_16x16x32_bf16 v[48:51], v[146:149], v[138:141], v[48:51]
	v_mfma_f32_16x16x32_bf16 v[52:55], v[150:153], v[138:141], v[52:55]
	v_mfma_f32_16x16x32_bf16 v[14:17], v[154:157], v[138:141], v[14:17]
	s_waitcnt vmcnt(0) lgkmcnt(0)
	s_barrier
	ds_read_b128 v[126:129], v221 offset:16384
	ds_read_b128 v[130:133], v221 offset:18432
	ds_read_b128 v[134:137], v221 offset:20480
	ds_read_b128 v[138:141], v221 offset:22528
	ds_read_b128 v[142:145], v223 offset:49152
	ds_read_b128 v[146:149], v223 offset:51200
	ds_read_b128 v[150:153], v223 offset:53248
	ds_read_b128 v[154:157], v223 offset:55296
	s_mov_b32 m0, s93
	v_mfma_f32_16x16x32_bf16 v[62:65], v[176:179], v[158:161], v[62:65]
	global_load_lds_dwordx4 v184, s[88:89]
	s_add_u32 m0, m0, 0x1000
	v_mfma_f32_16x16x32_bf16 v[66:69], v[180:183], v[158:161], v[66:69]
	global_load_lds_dwordx4 v214, s[88:89]
	s_add_u32 m0, m0, 0x1000
	v_mfma_f32_16x16x32_bf16 v[70:73], v[192:195], v[158:161], v[70:73]
	global_load_lds_dwordx4 v215, s[88:89]
	s_add_u32 m0, m0, 0x1000
	v_mfma_f32_16x16x32_bf16 v[2:5], v[210:213], v[158:161], v[2:5]
	global_load_lds_dwordx4 v216, s[88:89]
	s_add_u32 m0, m0, 0x5000
	v_mfma_f32_16x16x32_bf16 v[18:21], v[176:179], v[164:167], v[18:21]
	global_load_lds_dwordx4 v217, s[90:91]
	s_add_u32 m0, m0, 0x1000
	v_mfma_f32_16x16x32_bf16 v[28:31], v[180:183], v[164:167], v[28:31]
	global_load_lds_dwordx4 v218, s[90:91]
	s_add_u32 m0, m0, 0x1000
	v_mfma_f32_16x16x32_bf16 v[56:59], v[192:195], v[164:167], v[56:59]
	global_load_lds_dwordx4 v219, s[90:91]
	s_add_u32 m0, m0, 0x1000
	v_mfma_f32_16x16x32_bf16 v[10:13], v[210:213], v[164:167], v[10:13]
	global_load_lds_dwordx4 v220, s[90:91]
	v_mfma_f32_16x16x32_bf16 v[22:25], v[176:179], v[168:171], v[22:25]
	s_add_u32 s88, s88, 0x80
	v_mfma_f32_16x16x32_bf16 v[32:35], v[180:183], v[168:171], v[32:35]
	s_addc_u32 s89, s89, 0
	v_mfma_f32_16x16x32_bf16 v[74:77], v[192:195], v[168:171], v[74:77]
	s_add_u32 s90, s90, 0x80
	v_mfma_f32_16x16x32_bf16 v[36:39], v[210:213], v[168:171], v[36:39]
	s_addc_u32 s91, s91, 0
	v_mfma_f32_16x16x32_bf16 v[44:47], v[176:179], v[172:175], v[44:47]
	v_mfma_f32_16x16x32_bf16 v[48:51], v[180:183], v[172:175], v[48:51]
	v_mfma_f32_16x16x32_bf16 v[52:55], v[192:195], v[172:175], v[52:55]
	v_mfma_f32_16x16x32_bf16 v[14:17], v[210:213], v[172:175], v[14:17]
	ds_read_b128 v[158:161], v222 offset:16384
	ds_read_b128 v[164:167], v222 offset:18432
	ds_read_b128 v[168:171], v222 offset:20480
	ds_read_b128 v[172:175], v222 offset:22528
	ds_read_b128 v[176:179], v224 offset:49152
	ds_read_b128 v[180:183], v224 offset:51200
	ds_read_b128 v[192:195], v224 offset:53248
	ds_read_b128 v[210:213], v224 offset:55296
	s_waitcnt lgkmcnt(8)
	v_mfma_f32_16x16x32_bf16 v[62:65], v[142:145], v[126:129], v[62:65]
	v_mfma_f32_16x16x32_bf16 v[66:69], v[146:149], v[126:129], v[66:69]
	v_mfma_f32_16x16x32_bf16 v[70:73], v[150:153], v[126:129], v[70:73]
	v_mfma_f32_16x16x32_bf16 v[2:5], v[154:157], v[126:129], v[2:5]
	v_mfma_f32_16x16x32_bf16 v[18:21], v[142:145], v[130:133], v[18:21]
	v_mfma_f32_16x16x32_bf16 v[28:31], v[146:149], v[130:133], v[28:31]
	v_mfma_f32_16x16x32_bf16 v[56:59], v[150:153], v[130:133], v[56:59]
	v_mfma_f32_16x16x32_bf16 v[10:13], v[154:157], v[130:133], v[10:13]
	v_mfma_f32_16x16x32_bf16 v[22:25], v[142:145], v[134:137], v[22:25]
	v_mfma_f32_16x16x32_bf16 v[32:35], v[146:149], v[134:137], v[32:35]
	v_mfma_f32_16x16x32_bf16 v[74:77], v[150:153], v[134:137], v[74:77]
	v_mfma_f32_16x16x32_bf16 v[36:39], v[154:157], v[134:137], v[36:39]
	v_mfma_f32_16x16x32_bf16 v[44:47], v[142:145], v[138:141], v[44:47]
	v_mfma_f32_16x16x32_bf16 v[48:51], v[146:149], v[138:141], v[48:51]
	v_mfma_f32_16x16x32_bf16 v[52:55], v[150:153], v[138:141], v[52:55]
	v_mfma_f32_16x16x32_bf16 v[14:17], v[154:157], v[138:141], v[14:17]
	s_waitcnt vmcnt(0) lgkmcnt(0)
	s_barrier
; #define G_MMA(ks_) __builtin_amdgcn_s_setprio(1); _Pragma("unroll") for (int m = 0; m < 4; ++m) \
;         _Pragma("unroll") for (int n = 0; n < 4; ++n) acc[m][n] = __builtin_amdgcn_mfma_f32_16x16x32_bf16(bfv##ks_[n], af##ks_[m], acc[m][n], 0, 0, 0); __builtin_amdgcn_s_setprio(0);
; template <class Epi>
; DEV void gemm_tile(const bf16_t* __restrict__ A, int lda, const bf16_t* __restrict__ Bt, int ldb, int K, int tm, int tn, char* smem, const Epi& epi) {
;     ...
;     const int nk = K >> 6;
;     G_DMA(0, 0);
;     asm volatile("s_waitcnt vmcnt(0)" ::: "memory");
;     __syncthreads();
; #pragma unroll 4
;     for (int kt = 0; kt < nk; ++kt) {
;         const int cur = kt & 1;
;         if (kt + 1 < nk) G_DMA(cur ^ 1, kt + 1);
;         {
;             G_FRAGS(cur, 0)
;             G_MMA(0)
;             G_FRAGS(cur, 1)
;             G_MMA(1)
;         }
;         asm volatile("s_waitcnt vmcnt(0)" ::: "memory");
;         __syncthreads();
;     }
	ds_read_b128 v[126:129], v221
	ds_read_b128 v[130:133], v221 offset:2048
	ds_read_b128 v[134:137], v221 offset:4096
	ds_read_b128 v[138:141], v221 offset:6144
	ds_read_b128 v[142:145], v223 offset:32768
	ds_read_b128 v[146:149], v223 offset:34816
	ds_read_b128 v[150:153], v223 offset:36864
	ds_read_b128 v[154:157], v223 offset:38912
	s_mov_b32 m0, s94
	v_mfma_f32_16x16x32_bf16 v[62:65], v[176:179], v[158:161], v[62:65]
	global_load_lds_dwordx4 v184, s[88:89]
	s_add_u32 m0, m0, 0x1000
	v_mfma_f32_16x16x32_bf16 v[66:69], v[180:183], v[158:161], v[66:69]
	global_load_lds_dwordx4 v214, s[88:89]
	s_add_u32 m0, m0, 0x1000
	v_mfma_f32_16x16x32_bf16 v[70:73], v[192:195], v[158:161], v[70:73]
	global_load_lds_dwordx4 v215, s[88:89]
	s_add_u32 m0, m0, 0x1000
	v_mfma_f32_16x16x32_bf16 v[2:5], v[210:213], v[158:161], v[2:5]
	global_load_lds_dwordx4 v216, s[88:89]
	s_add_u32 m0, m0, 0x5000
	v_mfma_f32_16x16x32_bf16 v[18:21], v[176:179], v[164:167], v[18:21]
	global_load_lds_dwordx4 v217, s[90:91]
	s_add_u32 m0, m0, 0x1000
	v_mfma_f32_16x16x32_bf16 v[28:31], v[180:183], v[164:167], v[28:31]
	global_load_lds_dwordx4 v218, s[90:91]
	s_add_u32 m0, m0, 0x1000
	v_mfma_f32_16x16x32_bf16 v[56:59], v[192:195], v[164:167], v[56:59]
	global_load_lds_dwordx4 v219, s[90:91]
	s_add_u32 m0, m0, 0x1000
	v_mfma_f32_16x16x32_bf16 v[10:13], v[210:213], v[164:167], v[10:13]
	global_load_lds_dwordx4 v220, s[90:91]
	v_mfma_f32_16x16x32_bf16 v[22:25], v[176:179], v[168:171], v[22:25]
	s_add_u32 s88, s88, 0x80
	v_mfma_f32_16x16x32_bf16 v[32:35], v[180:183], v[168:171], v[32:35]
	s_addc_u32 s89, s89, 0
	v_mfma_f32_16x16x32_bf16 v[74:77], v[192:195], v[168:171], v[74:77]
	s_add_u32 s90, s90, 0x80
	v_mfma_f32_16x16x32_bf16 v[36:39], v[210:213], v[168:171], v[36:39]
	s_addc_u32 s91, s91, 0
	v_mfma_f32_16x16x32_bf16 v[44:47], v[176:179], v[172:175], v[44:47]
	v_mfma_f32_16x16x32_bf16 v[48:51], v[180:183], v[172:175], v[48:51]
	v_mfma_f32_16x16x32_bf16 v[52:55], v[192:195], v[172:175], v[52:55]
	v_mfma_f32_16x16x32_bf16 v[14:17], v[210:213], v[172:175], v[14:17]
	s_sub_u32 s92, s92, 1
	s_cmp_lg_u32 s92, 0
	s_cbranch_scc1 .Lgemm_out_loop
	ds_read_b128 v[158:161], v222
	ds_read_b128 v[164:167], v222 offset:2048
	ds_read_b128 v[168:171], v222 offset:4096
	ds_read_b128 v[172:175], v222 offset:6144
	ds_read_b128 v[176:179], v224 offset:32768
	ds_read_b128 v[180:183], v224 offset:34816
	ds_read_b128 v[192:195], v224 offset:36864
	ds_read_b128 v[210:213], v224 offset:38912
	s_waitcnt lgkmcnt(8)
	v_mfma_f32_16x16x32_bf16 v[62:65], v[142:145], v[126:129], v[62:65]
	v_mfma_f32_16x16x32_bf16 v[66:69], v[146:149], v[126:129], v[66:69]
	v_mfma_f32_16x16x32_bf16 v[70:73], v[150:153], v[126:129], v[70:73]
	v_mfma_f32_16x16x32_bf16 v[2:5], v[154:157], v[126:129], v[2:5]
	v_mfma_f32_16x16x32_bf16 v[18:21], v[142:145], v[130:133], v[18:21]
	v_mfma_f32_16x16x32_bf16 v[28:31], v[146:149], v[130:133], v[28:31]
	v_mfma_f32_16x16x32_bf16 v[56:59], v[150:153], v[130:133], v[56:59]
	v_mfma_f32_16x16x32_bf16 v[10:13], v[154:157], v[130:133], v[10:13]
	v_mfma_f32_16x16x32_bf16 v[22:25], v[142:145], v[134:137], v[22:25]
	v_mfma_f32_16x16x32_bf16 v[32:35], v[146:149], v[134:137], v[32:35]
	v_mfma_f32_16x16x32_bf16 v[74:77], v[150:153], v[134:137], v[74:77]
	v_mfma_f32_16x16x32_bf16 v[36:39], v[154:157], v[134:137], v[36:39]
	v_mfma_f32_16x16x32_bf16 v[44:47], v[142:145], v[138:141], v[44:47]
	v_mfma_f32_16x16x32_bf16 v[48:51], v[146:149], v[138:141], v[48:51]
	v_mfma_f32_16x16x32_bf16 v[52:55], v[150:153], v[138:141], v[52:55]
	v_mfma_f32_16x16x32_bf16 v[14:17], v[154:157], v[138:141], v[14:17]
	s_waitcnt vmcnt(0) lgkmcnt(0)
	s_barrier
	ds_read_b128 v[126:129], v221 offset:16384
	ds_read_b128 v[130:133], v221 offset:18432
	ds_read_b128 v[134:137], v221 offset:20480
	ds_read_b128 v[138:141], v221 offset:22528
	ds_read_b128 v[142:145], v223 offset:49152
	ds_read_b128 v[146:149], v223 offset:51200
	ds_read_b128 v[150:153], v223 offset:53248
	ds_read_b128 v[154:157], v223 offset:55296
	v_mfma_f32_16x16x32_bf16 v[62:65], v[176:179], v[158:161], v[62:65]
	v_mfma_f32_16x16x32_bf16 v[66:69], v[180:183], v[158:161], v[66:69]
	v_mfma_f32_16x16x32_bf16 v[70:73], v[192:195], v[158:161], v[70:73]
	v_mfma_f32_16x16x32_bf16 v[2:5], v[210:213], v[158:161], v[2:5]
	v_mfma_f32_16x16x32_bf16 v[18:21], v[176:179], v[164:167], v[18:21]
	v_mfma_f32_16x16x32_bf16 v[28:31], v[180:183], v[164:167], v[28:31]
	v_mfma_f32_16x16x32_bf16 v[56:59], v[192:195], v[164:167], v[56:59]
	v_mfma_f32_16x16x32_bf16 v[10:13], v[210:213], v[164:167], v[10:13]
	v_mfma_f32_16x16x32_bf16 v[22:25], v[176:179], v[168:171], v[22:25]
	v_mfma_f32_16x16x32_bf16 v[32:35], v[180:183], v[168:171], v[32:35]
	v_mfma_f32_16x16x32_bf16 v[74:77], v[192:195], v[168:171], v[74:77]
	v_mfma_f32_16x16x32_bf16 v[36:39], v[210:213], v[168:171], v[36:39]
	v_mfma_f32_16x16x32_bf16 v[44:47], v[176:179], v[172:175], v[44:47]
	v_mfma_f32_16x16x32_bf16 v[48:51], v[180:183], v[172:175], v[48:51]
	v_mfma_f32_16x16x32_bf16 v[52:55], v[192:195], v[172:175], v[52:55]
	v_mfma_f32_16x16x32_bf16 v[14:17], v[210:213], v[172:175], v[14:17]
	ds_read_b128 v[158:161], v222 offset:16384
	ds_read_b128 v[164:167], v222 offset:18432
	ds_read_b128 v[168:171], v222 offset:20480
	ds_read_b128 v[172:175], v222 offset:22528
	ds_read_b128 v[176:179], v224 offset:49152
	ds_read_b128 v[180:183], v224 offset:51200
	ds_read_b128 v[192:195], v224 offset:53248
	ds_read_b128 v[210:213], v224 offset:55296
	s_waitcnt lgkmcnt(8)
	v_mfma_f32_16x16x32_bf16 v[62:65], v[142:145], v[126:129], v[62:65]
	v_mfma_f32_16x16x32_bf16 v[66:69], v[146:149], v[126:129], v[66:69]
	v_mfma_f32_16x16x32_bf16 v[70:73], v[150:153], v[126:129], v[70:73]
	v_mfma_f32_16x16x32_bf16 v[2:5], v[154:157], v[126:129], v[2:5]
	v_mfma_f32_16x16x32_bf16 v[18:21], v[142:145], v[130:133], v[18:21]
	v_mfma_f32_16x16x32_bf16 v[28:31], v[146:149], v[130:133], v[28:31]
	v_mfma_f32_16x16x32_bf16 v[56:59], v[150:153], v[130:133], v[56:59]
	v_mfma_f32_16x16x32_bf16 v[10:13], v[154:157], v[130:133], v[10:13]
	v_mfma_f32_16x16x32_bf16 v[22:25], v[142:145], v[134:137], v[22:25]
	v_mfma_f32_16x16x32_bf16 v[32:35], v[146:149], v[134:137], v[32:35]
	v_mfma_f32_16x16x32_bf16 v[74:77], v[150:153], v[134:137], v[74:77]
	v_mfma_f32_16x16x32_bf16 v[36:39], v[154:157], v[134:137], v[36:39]
	v_mfma_f32_16x16x32_bf16 v[44:47], v[142:145], v[138:141], v[44:47]
	v_mfma_f32_16x16x32_bf16 v[48:51], v[146:149], v[138:141], v[48:51]
	v_mfma_f32_16x16x32_bf16 v[52:55], v[150:153], v[138:141], v[52:55]
	v_mfma_f32_16x16x32_bf16 v[14:17], v[154:157], v[138:141], v[14:17]
	s_waitcnt lgkmcnt(0)
	s_barrier
; DEV int tid_() { int t = __builtin_amdgcn_workitem_id_x(); asm volatile("" : "+v"(t)); return t; }
; #define G_MMA(ks_) __builtin_amdgcn_s_setprio(1); _Pragma("unroll") for (int m = 0; m < 4; ++m) \
;         _Pragma("unroll") for (int n = 0; n < 4; ++n) acc[m][n] = __builtin_amdgcn_mfma_f32_16x16x32_bf16(bfv##ks_[n], af##ks_[m], acc[m][n], 0, 0, 0); __builtin_amdgcn_s_setprio(0);
; template <class Epi>
; DEV void gemm_tile(const bf16_t* __restrict__ A, int lda, const bf16_t* __restrict__ Bt, int ldb, int K, int tm, int tn, char* smem, const Epi& epi) {
;     ...
;             G_MMA(1)
;         }
;         asm volatile("s_waitcnt vmcnt(0)" ::: "memory");
;         __syncthreads();
;     }
;     ...
;     float* Ct = (float*)smem;
; #pragma unroll
;     for (int m = 0; m < 4; ++m)
; #pragma unroll
;         for (int n = 0; n < 4; ++n) *(f32x4*)(Ct + (wr * 64 + m * 16 + fr) * CP + wc * 64 + n * 16 + fq * 4) = acc[m][n];
;     __syncthreads();
;     DEV void operator()(int tm, int tn, const float* Ct) const {
;         const int row0 = tm * 128, b = row0 / TT, tt0 = row0 - b * TT;
;         const int tid = tid_(), c = (tid & 31) << 2, rb = tid >> 5;
;         const f32x4 g = *(const f32x4*)(mod + (size_t)(tt0 < SEQ ? b : 32) * 6144 + goff + tn * 128 + c);
;         float* x0 = xrow(*p, row0) + tn * 128 + c;
;         const float* xs = from_in ? xrow_in(*p, row0) + tn * 128 + c : x0;
; #pragma unroll
;         for (int it0 = 0; it0 < 16; it0 += 8) {
;             f32x4 xv[8];
; #pragma unroll
;             for (int u = 0; u < 8; ++u) xv[u] = *(const f32x4*)(xs + (size_t)(rb + 8 * (it0 + u)) * D);
	v_mfma_f32_16x16x32_bf16 v[62:65], v[176:179], v[158:161], v[62:65]
	v_mfma_f32_16x16x32_bf16 v[66:69], v[180:183], v[158:161], v[66:69]
	v_mfma_f32_16x16x32_bf16 v[70:73], v[192:195], v[158:161], v[70:73]
	v_mfma_f32_16x16x32_bf16 v[2:5], v[210:213], v[158:161], v[2:5]
	v_mfma_f32_16x16x32_bf16 v[18:21], v[176:179], v[164:167], v[18:21]
	v_mfma_f32_16x16x32_bf16 v[28:31], v[180:183], v[164:167], v[28:31]
	v_mfma_f32_16x16x32_bf16 v[56:59], v[192:195], v[164:167], v[56:59]
	v_mfma_f32_16x16x32_bf16 v[10:13], v[210:213], v[164:167], v[10:13]
	v_mfma_f32_16x16x32_bf16 v[22:25], v[176:179], v[168:171], v[22:25]
	v_mfma_f32_16x16x32_bf16 v[32:35], v[180:183], v[168:171], v[32:35]
	v_mfma_f32_16x16x32_bf16 v[74:77], v[192:195], v[168:171], v[74:77]
	v_mfma_f32_16x16x32_bf16 v[36:39], v[210:213], v[168:171], v[36:39]
	v_mfma_f32_16x16x32_bf16 v[44:47], v[176:179], v[172:175], v[44:47]
	v_mfma_f32_16x16x32_bf16 v[48:51], v[180:183], v[172:175], v[48:51]
	v_mfma_f32_16x16x32_bf16 v[52:55], v[192:195], v[172:175], v[52:55]
	v_mfma_f32_16x16x32_bf16 v[14:17], v[210:213], v[172:175], v[14:17]
	s_setprio 0
	v_readlane_b32 s88, v255, 24
	v_readlane_b32 s89, v255, 25
	v_readlane_b32 s90, v255, 26
	v_readlane_b32 s91, v255, 27
	v_readlane_b32 s92, v255, 28
	v_readlane_b32 s93, v255, 29
	v_readlane_b32 s94, v255, 30
	v_readlane_b32 s95, v255, 31
	s_nop 7
	s_nop 1
	s_mul_hi_u32 s43, s43, 0x38e38e39
	s_lshr_b32 s94, s43, 2
	s_mul_i32 s43, s94, 0xfffff700
	s_add_i32 s48, s43, s42
	s_cmpk_lt_i32 s48, 0x800
	s_cselect_b64 s[42:43], -1, 0
	s_mul_i32 s45, s94, 0x6000
	s_and_b64 s[46:47], s[42:43], exec
	v_lshl_or_b32 v7, v8, 6, v7
	s_cselect_b32 s45, s45, 0xc0000
	v_lshl_add_u32 v6, v6, 8, 16
	v_lshlrev_b32_e32 v0, 4, v0
	v_mul_lo_u32 v7, v7, s58
	s_add_u32 s45, s10, s45
	v_add3_u32 v0, v6, v0, v7
	v_mov_b32_e32 v6, v163
	s_addc_u32 s46, s11, 0
	s_lshl_b32 s47, s44, 2
	s_waitcnt vmcnt(0)
	s_barrier
	ds_write_b128 v0, v[62:65]
	ds_write_b128 v0, v[66:69] offset:64
	ds_write_b128 v0, v[70:73] offset:128
	ds_write_b128 v0, v[2:5] offset:192
	ds_write_b128 v0, v[18:21] offset:8448
	ds_write_b128 v0, v[28:31] offset:8512
	ds_write_b128 v0, v[56:59] offset:8576
	ds_write_b128 v0, v[10:13] offset:8640
	ds_write_b128 v0, v[22:25] offset:16896
	ds_write_b128 v0, v[32:35] offset:16960
	ds_write_b128 v0, v[74:77] offset:17024
	ds_write_b128 v0, v[36:39] offset:17088
	ds_write_b128 v0, v[44:47] offset:25344
	ds_write_b128 v0, v[48:51] offset:25408
	ds_write_b128 v0, v[52:55] offset:25472
	ds_write_b128 v0, v[14:17] offset:25536
	s_waitcnt lgkmcnt(0)
	s_barrier
	s_add_u32 s44, s45, s47
	v_lshlrev_b32_e32 v0, 4, v6
	s_addc_u32 s45, s46, 0
	v_and_b32_e32 v0, 0x1f0, v0
	v_lshl_add_u64 v[2:3], s[44:45], 0, v[0:1]
	s_movk_i32 s44, 0x2000
	s_add_i32 s46, s48, 0xfffff800
	s_ashr_i32 s49, s48, 31
	v_add_co_u32_e32 v2, vcc, s44, v2
	s_and_b64 s[44:45], s[42:43], exec
	v_readlane_b32 s64, v251, 1
	v_readlane_b32 s67, v251, 4
	v_readlane_b32 s44, v251, 36
	s_cselect_b32 s50, 23, 20
	v_readlane_b32 s66, v251, 3
	s_cselect_b32 s51, s67, s44
	v_readlane_b32 s44, v251, 35
	s_cselect_b32 s52, s66, s44
	s_cselect_b32 s45, s49, 0
	s_cselect_b32 s44, s48, s46
	s_lshl_b32 s46, s94, s50
	s_add_u32 s46, s52, s46
	s_addc_u32 s48, s51, 0
	s_lshl_b64 s[44:45], s[44:45], 12
	s_add_u32 s49, s46, s44
	s_addc_u32 s51, s48, s45
	s_and_b64 s[42:43], s[42:43], exec
	s_cselect_b32 s52, s69, s73
	s_cselect_b32 s53, s68, s72
	s_lshl_b64 s[42:43], s[94:95], s50
	s_add_u32 s50, s53, s42
	s_addc_u32 s52, s52, s43
	s_and_b64 s[42:43], s[6:7], exec
	s_cselect_b32 s43, s46, s50
	s_cselect_b32 s42, s48, s52
	s_add_u32 s44, s43, s44
	s_addc_u32 s45, s42, s45
	s_add_u32 s42, s49, s47
	s_addc_u32 s43, s51, 0
	v_lshl_add_u64 v[14:15], s[42:43], 0, v[0:1]
	v_ashrrev_i32_e32 v48, 5, v6
	s_add_u32 s42, s44, s47
	s_addc_u32 s43, s45, 0
	v_ashrrev_i32_e32 v49, 31, v48
	v_lshl_add_u64 v[16:17], s[42:43], 0, v[0:1]
	v_lshlrev_b64 v[18:19], 12, v[48:49]
	v_addc_co_u32_e32 v3, vcc, 0, v3, vcc
	v_lshl_add_u64 v[6:7], v[16:17], 0, v[18:19]
	global_load_dwordx4 v[2:5], v[2:3], off
	s_mov_b64 s[42:43], 0x8000
	global_load_dwordx4 v[24:27], v[6:7], off
	v_lshl_add_u64 v[52:53], v[18:19], 0, s[42:43]
	v_lshl_add_u64 v[6:7], v[16:17], 0, v[52:53]
	global_load_dwordx4 v[28:31], v[6:7], off
	v_lshl_add_u64 v[54:55], v[18:19], 0, s[90:91]
	v_lshl_add_u64 v[6:7], v[16:17], 0, v[54:55]
	global_load_dwordx4 v[32:35], v[6:7], off
	s_mov_b64 s[42:43], 0x18000
	v_lshl_add_u64 v[56:57], v[18:19], 0, s[42:43]
	v_lshl_add_u64 v[6:7], v[16:17], 0, v[56:57]
	global_load_dwordx4 v[36:39], v[6:7], off
	v_lshl_add_u64 v[58:59], v[18:19], 0, s[92:93]
	v_lshl_add_u64 v[6:7], v[16:17], 0, v[58:59]
	global_load_dwordx4 v[40:43], v[6:7], off
	s_mov_b64 s[42:43], 0x28000
	v_lshl_add_u64 v[60:61], v[18:19], 0, s[42:43]
	v_lshl_add_u64 v[6:7], v[16:17], 0, v[60:61]
	global_load_dwordx4 v[44:47], v[6:7], off
	v_lshl_add_u64 v[22:23], v[18:19], 0, s[0:1]
	v_lshl_add_u64 v[6:7], v[16:17], 0, v[22:23]
	global_load_dwordx4 v[10:13], v[6:7], off
	s_mov_b64 s[0:1], 0x38000
	v_lshl_add_u64 v[20:21], v[18:19], 0, s[0:1]
	v_lshl_add_u64 v[6:7], v[16:17], 0, v[20:21]
	global_load_dwordx4 v[6:9], v[6:7], off
	v_mul_lo_u32 v48, v48, s58
	v_add3_u32 v0, 16, v0, v48
	ds_read_b128 v[48:51], v0
	v_lshl_add_u64 v[22:23], v[14:15], 0, v[22:23]
	s_mov_b64 s[0:1], 0x40000
	s_mov_b64 s[42:43], 0x48000
	v_readlane_b32 s65, v251, 2
	s_waitcnt vmcnt(7) lgkmcnt(0)
;     DEV void operator()(int tm, int tn, const float* Ct) const {
;     ...
; #pragma unroll
;         for (int it0 = 0; it0 < 16; it0 += 8) {
;             f32x4 xv[8];
; #pragma unroll
;             for (int u = 0; u < 8; ++u) xv[u] = *(const f32x4*)(xs + (size_t)(rb + 8 * (it0 + u)) * D);
; #pragma unroll
;             for (int u = 0; u < 8; ++u) { const int r = rb + 8 * (it0 + u); *(f32x4*)(x0 + (size_t)r * D) = xv[u] + g * *(const f32x4*)(Ct + r * CP + c); }
;         }
	v_pk_fma_f32 v[26:27], v[4:5], v[50:51], v[26:27]
	v_pk_fma_f32 v[24:25], v[2:3], v[48:49], v[24:25]
	v_lshl_add_u64 v[48:49], v[14:15], 0, v[18:19]
	global_store_dwordx4 v[48:49], v[24:27], off
	ds_read_b128 v[24:27], v0 offset:4224
	v_lshl_add_u64 v[50:51], v[18:19], 0, s[0:1]
	s_mov_b64 s[0:1], 0x50000
	s_waitcnt vmcnt(7) lgkmcnt(0)
	v_pk_fma_f32 v[26:27], v[4:5], v[26:27], v[30:31]
	v_pk_fma_f32 v[24:25], v[2:3], v[24:25], v[28:29]
	v_lshl_add_u64 v[28:29], v[14:15], 0, v[52:53]
	global_store_dwordx4 v[28:29], v[24:27], off
	ds_read_b128 v[24:27], v0 offset:8448
	v_lshl_add_u64 v[28:29], v[14:15], 0, v[54:55]
	v_lshl_add_u64 v[52:53], v[18:19], 0, s[42:43]
	v_lshl_add_u64 v[54:55], v[18:19], 0, s[0:1]
	s_mov_b64 s[0:1], 0x58000
	s_waitcnt vmcnt(7) lgkmcnt(0)
	v_pk_fma_f32 v[26:27], v[4:5], v[26:27], v[34:35]
	v_pk_fma_f32 v[24:25], v[2:3], v[24:25], v[32:33]
	global_store_dwordx4 v[28:29], v[24:27], off
	ds_read_b128 v[24:27], v0 offset:12672
	v_lshl_add_u64 v[28:29], v[14:15], 0, v[56:57]
	v_lshl_add_u64 v[56:57], v[18:19], 0, s[0:1]
	s_mov_b64 s[0:1], 0x60000
	s_waitcnt vmcnt(7) lgkmcnt(0)
	v_pk_fma_f32 v[26:27], v[4:5], v[26:27], v[38:39]
	v_pk_fma_f32 v[24:25], v[2:3], v[24:25], v[36:37]
	global_store_dwordx4 v[28:29], v[24:27], off
	ds_read_b128 v[24:27], v0 offset:16896
	v_lshl_add_u64 v[28:29], v[14:15], 0, v[58:59]
	v_lshl_add_u64 v[58:59], v[18:19], 0, s[0:1]
	s_mov_b64 s[0:1], 0x68000
	s_waitcnt vmcnt(7) lgkmcnt(0)
	v_pk_fma_f32 v[26:27], v[4:5], v[26:27], v[42:43]
	v_pk_fma_f32 v[24:25], v[2:3], v[24:25], v[40:41]
	global_store_dwordx4 v[28:29], v[24:27], off
	ds_read_b128 v[24:27], v0 offset:21120
	v_lshl_add_u64 v[28:29], v[14:15], 0, v[60:61]
	v_lshl_add_u64 v[60:61], v[18:19], 0, s[0:1]
	s_mov_b64 s[0:1], 0x70000
	s_waitcnt vmcnt(7) lgkmcnt(0)
	v_pk_fma_f32 v[26:27], v[4:5], v[26:27], v[46:47]
	v_pk_fma_f32 v[24:25], v[2:3], v[24:25], v[44:45]
	global_store_dwordx4 v[28:29], v[24:27], off
	ds_read_b128 v[24:27], v0 offset:25344
	ds_read_b128 v[46:49], v0 offset:33792
	s_waitcnt vmcnt(7) lgkmcnt(1)
	v_pk_fma_f32 v[12:13], v[4:5], v[26:27], v[12:13]
	v_pk_fma_f32 v[10:11], v[2:3], v[24:25], v[10:11]
	global_store_dwordx4 v[22:23], v[10:13], off
	ds_read_b128 v[10:13], v0 offset:29568
	s_waitcnt vmcnt(7) lgkmcnt(0)
	v_pk_fma_f32 v[8:9], v[4:5], v[12:13], v[8:9]
	v_pk_fma_f32 v[6:7], v[2:3], v[10:11], v[6:7]
	v_lshl_add_u64 v[10:11], v[14:15], 0, v[20:21]
	global_store_dwordx4 v[10:11], v[6:9], off
	v_lshl_add_u64 v[20:21], v[18:19], 0, s[0:1]
	s_mov_b64 s[0:1], 0x78000
	v_lshl_add_u64 v[6:7], v[16:17], 0, v[50:51]
	global_load_dwordx4 v[22:25], v[6:7], off
	v_lshl_add_u64 v[6:7], v[16:17], 0, v[52:53]
	global_load_dwordx4 v[26:29], v[6:7], off
	v_lshl_add_u64 v[6:7], v[16:17], 0, v[54:55]
	global_load_dwordx4 v[30:33], v[6:7], off
	v_lshl_add_u64 v[6:7], v[16:17], 0, v[56:57]
	global_load_dwordx4 v[34:37], v[6:7], off
	v_lshl_add_u64 v[6:7], v[16:17], 0, v[58:59]
	global_load_dwordx4 v[38:41], v[6:7], off
	v_lshl_add_u64 v[6:7], v[16:17], 0, v[60:61]
	global_load_dwordx4 v[42:45], v[6:7], off
	v_lshl_add_u64 v[6:7], v[16:17], 0, v[20:21]
	global_load_dwordx4 v[10:13], v[6:7], off
	v_lshl_add_u64 v[18:19], v[18:19], 0, s[0:1]
	v_lshl_add_u64 v[6:7], v[16:17], 0, v[18:19]
	global_load_dwordx4 v[6:9], v[6:7], off
	v_lshl_add_u64 v[16:17], v[14:15], 0, v[50:51]
	s_waitcnt vmcnt(7)
	v_pk_fma_f32 v[24:25], v[4:5], v[48:49], v[24:25]
	v_pk_fma_f32 v[22:23], v[2:3], v[46:47], v[22:23]
	global_store_dwordx4 v[16:17], v[22:25], off
	ds_read_b128 v[22:25], v0 offset:38016
	v_lshl_add_u64 v[16:17], v[14:15], 0, v[52:53]
	s_waitcnt vmcnt(7) lgkmcnt(0)
	v_pk_fma_f32 v[24:25], v[4:5], v[24:25], v[28:29]
	v_pk_fma_f32 v[22:23], v[2:3], v[22:23], v[26:27]
	global_store_dwordx4 v[16:17], v[22:25], off
	ds_read_b128 v[22:25], v0 offset:42240
	v_lshl_add_u64 v[16:17], v[14:15], 0, v[54:55]
	s_waitcnt vmcnt(7) lgkmcnt(0)
	v_pk_fma_f32 v[24:25], v[4:5], v[24:25], v[32:33]
	v_pk_fma_f32 v[22:23], v[2:3], v[22:23], v[30:31]
	global_store_dwordx4 v[16:17], v[22:25], off
	ds_read_b128 v[22:25], v0 offset:46464
	v_lshl_add_u64 v[16:17], v[14:15], 0, v[56:57]
	s_waitcnt vmcnt(7) lgkmcnt(0)
	v_pk_fma_f32 v[24:25], v[4:5], v[24:25], v[36:37]
	v_pk_fma_f32 v[22:23], v[2:3], v[22:23], v[34:35]
	global_store_dwordx4 v[16:17], v[22:25], off
	ds_read_b128 v[22:25], v0 offset:50688
	v_lshl_add_u64 v[16:17], v[14:15], 0, v[58:59]
	s_waitcnt vmcnt(7) lgkmcnt(0)
	v_pk_fma_f32 v[24:25], v[4:5], v[24:25], v[40:41]
	v_pk_fma_f32 v[22:23], v[2:3], v[22:23], v[38:39]
	global_store_dwordx4 v[16:17], v[22:25], off
	ds_read_b128 v[22:25], v0 offset:54912
	v_lshl_add_u64 v[16:17], v[14:15], 0, v[60:61]
	s_waitcnt vmcnt(7) lgkmcnt(0)
	v_pk_fma_f32 v[24:25], v[4:5], v[24:25], v[44:45]
	v_pk_fma_f32 v[22:23], v[2:3], v[22:23], v[42:43]
	global_store_dwordx4 v[16:17], v[22:25], off
	ds_read_b128 v[22:25], v0 offset:59136
	v_lshl_add_u64 v[16:17], v[14:15], 0, v[20:21]
	s_waitcnt vmcnt(7) lgkmcnt(0)
	v_pk_fma_f32 v[12:13], v[4:5], v[24:25], v[12:13]
	v_pk_fma_f32 v[10:11], v[2:3], v[22:23], v[10:11]
	global_store_dwordx4 v[16:17], v[10:13], off
	ds_read_b128 v[10:13], v0 offset:63360
	s_waitcnt vmcnt(7) lgkmcnt(0)
	v_pk_fma_f32 v[4:5], v[4:5], v[12:13], v[8:9]
	v_pk_fma_f32 v[2:3], v[2:3], v[10:11], v[6:7]
	v_lshl_add_u64 v[6:7], v[14:15], 0, v[18:19]
	global_store_dwordx4 v[6:7], v[2:5], off
	s_barrier
	s_branch .LBB0_161

; template <class Epi>
; DEV void gemm_tile(const bf16_t* __restrict__ A, int lda, const bf16_t* __restrict__ Bt, int ldb, int K, int tm, int tn, char* smem, const Epi& epi) {
;     ...
;     const int lrow = tid >> 3, lcc = (tid & 7) * 8, lsw = (((tid & 7) ^ (lrow & 7)) * 8);
;     const bf16_t* Ag = A + (size_t)(tm * 128 + lrow) * lda + lcc;
;     const bf16_t* Bg = Bt + (size_t)(tn * 128 + lrow) * ldb + lcc;
;     f32x4 acc[4][4];
; #pragma unroll
;     for (int m = 0; m < 4; ++m)
; #pragma unroll
;         for (int n = 0; n < 4; ++n) acc[m][n] = (f32x4){0.f, 0.f, 0.f, 0.f};
;     const int gsw = (((tid & 7) ^ (lrow & 7)) * 8);
;     const bf16_t* Ad = A + (size_t)(tm * 128 + lrow) * lda + gsw;
;     const bf16_t* Bd = Bt + (size_t)(tn * 128 + lrow) * ldb + gsw;
;     char* Asb = (char*)As; char* Bsb = (char*)Bs;
;     ...
;     const int nk = K >> 6;
;     G_DMA(0, 0);
;     asm volatile("s_waitcnt vmcnt(0)" ::: "memory");
;     __syncthreads();
; template <class Epi>
; DEV void gemm_phase(const bf16_t* A, int lda, const bf16_t* Bt, int ldb, int K, int ntm, int ntn, bool skip_ctx, char* smem, const Epi& epi) {
;     ...
;         for (int q = slot; q < per; q += nper) {
;             int tm, tn;
;             if (q < fullq) { const int tb = q / (R * 8), r = q - tb * (R * 8); tm = r >> 3; tn = tb * 8 + (r & 7); }
;             else { const int q2 = q - fullq; tm = q2 / w; tn = nfb * 8 + (q2 - tm * w); }
;             tm += xcd * R;
;             if (skip_ctx && ((tm * 128) % TT) >= SEQ) continue;
;             gemm_tile(A, lda, Bt, ldb, K, tm, tn, smem, epi);
.LBB0_179:
	s_lshr_b32 s39, s37, 3
	v_readlane_b32 s38, v253, 31
	s_add_i32 s39, s39, s38
	s_lshl_b32 s38, s39, 7
	s_mul_hi_u32 s42, s38, 0x38e38e39
	s_lshr_b32 s42, s42, 9
	s_mulk_i32 s42, 0x900
	s_sub_i32 s42, s38, s42
	s_cmpk_gt_u32 s42, 0x7ff
	s_cselect_b64 s[42:43], -1, 0
	s_and_b64 s[42:43], s[54:55], s[42:43]
	s_and_b64 vcc, exec, s[42:43]
	s_cbranch_vccnz .LBB0_178
	v_mov_b32_e32 v10, v163
	s_and_b32 s42, s36, 0x380
	s_waitcnt vmcnt(10)
	v_ashrrev_i32_e32 v0, 3, v10
	v_readlane_b32 s44, v251, 27
	v_add_u32_e32 v4, s38, v0
	v_add_u32_e32 v8, s42, v0
	v_xor_b32_e32 v0, v0, v10
	v_readlane_b32 s45, v251, 28
	v_lshlrev_b32_e32 v0, 4, v0
	v_lshl_add_u32 v14, v10, 4, 16
	v_mov_b64_e32 v[2:3], s[44:45]
	v_mad_i64_i32 v[2:3], s[44:45], v4, s29, v[2:3]
	v_mov_b64_e32 v[4:5], s[0:1]
	v_and_b32_e32 v0, 0x70, v0
	v_add_u32_e32 v13, 0x8000, v14
	v_readfirstlane_b32 s63, v14
	v_mad_i64_i32 v[8:9], s[44:45], v8, s29, v[4:5]
	v_lshl_add_u64 v[4:5], v[2:3], 0, v[0:1]
	s_mov_b32 m0, s63
	v_readfirstlane_b32 s51, v13
	v_add_u32_e32 v15, 0x1000, v14
	v_lshl_add_u64 v[2:3], v[8:9], 0, v[0:1]
	global_load_lds_dwordx4 v[4:5], off
	s_mov_b32 m0, s51
	s_mov_b64 s[44:45], 0x2c000
	v_readfirstlane_b32 s52, v15
	v_add_u32_e32 v16, 0x9000, v14
	global_load_lds_dwordx4 v[2:3], off
	v_lshl_add_u64 v[8:9], v[4:5], 0, s[44:45]
	s_mov_b32 m0, s52
	v_readfirstlane_b32 s53, v16
	v_add_u32_e32 v17, 0x2000, v14
	global_load_lds_dwordx4 v[8:9], off
	v_lshl_add_u64 v[8:9], v[2:3], 0, s[44:45]
	s_mov_b32 m0, s53
	s_mov_b64 s[44:45], 0x58000
	v_readfirstlane_b32 s62, v17
	s_waitcnt vmcnt(0)
	v_add_u32_e32 v18, 0xa000, v14
	global_load_lds_dwordx4 v[8:9], off
	v_lshl_add_u64 v[8:9], v[4:5], 0, s[44:45]
	s_mov_b32 m0, s62
	v_readfirstlane_b32 s64, v18
	v_add_u32_e32 v19, 0x3000, v14
	global_load_lds_dwordx4 v[8:9], off
	v_lshl_add_u64 v[8:9], v[2:3], 0, s[44:45]
	s_mov_b32 m0, s64
	s_mov_b64 s[44:45], 0x84000
	v_readfirstlane_b32 s65, v19
	v_add_u32_e32 v20, 0xb000, v14
	global_load_lds_dwordx4 v[8:9], off
	v_lshl_add_u64 v[8:9], v[4:5], 0, s[44:45]
	s_mov_b32 m0, s65
	v_readfirstlane_b32 s84, v20
	global_load_lds_dwordx4 v[8:9], off
	v_lshl_add_u64 v[8:9], v[2:3], 0, s[44:45]
	s_mov_b32 m0, s84
	v_and_b32_e32 v7, 15, v10
	global_load_lds_dwordx4 v[8:9], off
	v_ashrrev_i32_e32 v8, 7, v10
	v_bfe_u32 v6, v10, 6, 1
	v_lshlrev_b32_e32 v9, 13, v8
	v_lshlrev_b32_e32 v12, 7, v7
	v_add_u32_e32 v21, 0x4000, v14
	v_lshrrev_b32_e32 v11, 4, v10
	v_bfe_u32 v0, v10, 4, 2
	v_add3_u32 v29, 16, v9, v12
	v_and_b32_e32 v9, 7, v10
	v_lshlrev_b32_e32 v10, 13, v6
	s_mov_b64 s[44:45], 0x80
	v_add_u32_e32 v22, 0xc000, v14
	v_readfirstlane_b32 s47, v21
	v_bitop3_b32 v30, v11, v9, 3 bitop3:0x6c
	v_add3_u32 v12, 16, v10, v12
	v_lshl_add_u64 v[10:11], v[4:5], 0, s[44:45]
	s_mov_b32 m0, s47
	v_readfirstlane_b32 s43, v22
	s_waitcnt vmcnt(0)
	s_waitcnt vmcnt(0) lgkmcnt(0)
	s_barrier
	v_writelane_b32 v255, s88, 24
	v_writelane_b32 v255, s89, 25
	v_writelane_b32 v255, s90, 26
	v_writelane_b32 v255, s91, 27
	v_writelane_b32 v255, s92, 28
	v_writelane_b32 v255, s93, 29
	v_writelane_b32 v255, s94, 30
	v_writelane_b32 v255, s95, 31
	v_readfirstlane_b32 s88, v4
	v_readfirstlane_b32 s89, v5
	v_readfirstlane_b32 s90, v2
	v_readfirstlane_b32 s91, v3
	v_lshl_add_u32 v225, v163, 4, 16
	s_and_b32 s88, s88, 0xffffff80
	s_and_b32 s90, s90, 0xffffff80
	v_readfirstlane_b32 s93, v225
	v_subrev_u32_e32 v184, s88, v4
	v_subrev_u32_e32 v217, s90, v2
	v_add_u32_e32 v214, 0x2c000, v184
	v_add_u32_e32 v218, 0x2c000, v217
	v_add_u32_e32 v215, 0x58000, v184
	v_add_u32_e32 v219, 0x58000, v217
	v_add_u32_e32 v216, 0x84000, v184
	v_add_u32_e32 v220, 0x84000, v217
	s_add_u32 s94, s93, 0x4000
	s_add_u32 s88, s88, 0x80
	s_addc_u32 s89, s89, 0
	s_add_u32 s90, s90, 0x80
	s_addc_u32 s91, s91, 0
	v_and_b32_e32 v225, 15, v163
	v_lshlrev_b32_e32 v225, 7, v225
	v_bfe_u32 v226, v163, 4, 2
	v_and_b32_e32 v227, 7, v163
	v_xor_b32_e32 v226, v226, v227
	v_lshlrev_b32_e32 v227, 4, v226
	v_xor_b32_e32 v226, 4, v226
	v_lshlrev_b32_e32 v226, 4, v226
	v_lshrrev_b32_e32 v221, 7, v163
	v_lshl_add_u32 v221, v221, 13, v225
	v_add_u32_e32 v221, 16, v221
	v_bfe_u32 v223, v163, 6, 1
	v_lshl_add_u32 v223, v223, 13, v225
	v_add_u32_e32 v223, 16, v223
	v_add_u32_e32 v222, v221, v226
	v_add_u32_e32 v224, v223, v226
	v_add_u32_e32 v221, v221, v227
	v_add_u32_e32 v223, v223, v227
	v_mov_b32_e32 v62, 0
	v_mov_b32_e32 v63, 0
	v_mov_b32_e32 v64, 0
	v_mov_b32_e32 v65, 0
	v_mov_b32_e32 v66, 0
	v_mov_b32_e32 v67, 0
	v_mov_b32_e32 v68, 0
	v_mov_b32_e32 v69, 0
	v_mov_b32_e32 v70, 0
	v_mov_b32_e32 v71, 0
	v_mov_b32_e32 v72, 0
	v_mov_b32_e32 v73, 0
	v_mov_b32_e32 v2, 0
	v_mov_b32_e32 v3, 0
	v_mov_b32_e32 v4, 0
	v_mov_b32_e32 v5, 0
	v_mov_b32_e32 v14, 0
	v_mov_b32_e32 v15, 0
	v_mov_b32_e32 v16, 0
	v_mov_b32_e32 v17, 0
	v_mov_b32_e32 v22, 0
	v_mov_b32_e32 v23, 0
	v_mov_b32_e32 v24, 0
	v_mov_b32_e32 v25, 0
	v_mov_b32_e32 v30, 0
	v_mov_b32_e32 v31, 0
	v_mov_b32_e32 v32, 0
	v_mov_b32_e32 v33, 0
	v_mov_b32_e32 v18, 0
	v_mov_b32_e32 v19, 0
	v_mov_b32_e32 v20, 0
	v_mov_b32_e32 v21, 0
	v_mov_b32_e32 v26, 0
	v_mov_b32_e32 v27, 0
	v_mov_b32_e32 v28, 0
	v_mov_b32_e32 v29, 0
	v_mov_b32_e32 v34, 0
	v_mov_b32_e32 v35, 0
	v_mov_b32_e32 v36, 0
	v_mov_b32_e32 v37, 0
	v_mov_b32_e32 v58, 0
	v_mov_b32_e32 v59, 0
	v_mov_b32_e32 v60, 0
	v_mov_b32_e32 v61, 0
	v_mov_b32_e32 v38, 0
	v_mov_b32_e32 v39, 0
	v_mov_b32_e32 v40, 0
	v_mov_b32_e32 v41, 0
	v_mov_b32_e32 v46, 0
	v_mov_b32_e32 v47, 0
	v_mov_b32_e32 v48, 0
	v_mov_b32_e32 v49, 0
	v_mov_b32_e32 v50, 0
	v_mov_b32_e32 v51, 0
	v_mov_b32_e32 v52, 0
	v_mov_b32_e32 v53, 0
	v_mov_b32_e32 v54, 0
	v_mov_b32_e32 v55, 0
	v_mov_b32_e32 v56, 0
	v_mov_b32_e32 v57, 0
	v_mov_b32_e32 v10, 0
	v_mov_b32_e32 v11, 0
	v_mov_b32_e32 v12, 0
	v_mov_b32_e32 v13, 0
	s_mov_b32 m0, s94
	s_nop 0
	global_load_lds_dwordx4 v184, s[88:89]
	s_add_u32 m0, m0, 0x1000
	s_nop 0
	global_load_lds_dwordx4 v214, s[88:89]
	s_add_u32 m0, m0, 0x1000
	s_nop 0
	global_load_lds_dwordx4 v215, s[88:89]
	s_add_u32 m0, m0, 0x1000
	s_nop 0
	global_load_lds_dwordx4 v216, s[88:89]
	s_add_u32 m0, m0, 0x5000
	s_nop 0
	global_load_lds_dwordx4 v217, s[90:91]
	s_add_u32 m0, m0, 0x1000
	s_nop 0
	global_load_lds_dwordx4 v218, s[90:91]
	s_add_u32 m0, m0, 0x1000
	s_nop 0
	global_load_lds_dwordx4 v219, s[90:91]
	s_add_u32 m0, m0, 0x1000
	s_nop 0
	global_load_lds_dwordx4 v220, s[90:91]
	s_add_u32 s88, s88, 0x80
	s_addc_u32 s89, s89, 0
	s_add_u32 s90, s90, 0x80
	s_addc_u32 s91, s91, 0
	ds_read_b128 v[126:129], v221
	ds_read_b128 v[130:133], v221 offset:2048
	ds_read_b128 v[134:137], v221 offset:4096
	ds_read_b128 v[138:141], v221 offset:6144
	ds_read_b128 v[142:145], v223 offset:32768
	ds_read_b128 v[146:149], v223 offset:34816
	ds_read_b128 v[150:153], v223 offset:36864
	ds_read_b128 v[154:157], v223 offset:38912
	v_readlane_b32 s95, v251, 0
	s_nop 0
	s_cmp_lt_u32 s95, 0x100
	s_cbranch_scc1 .Lgemm_down_lowprio
	s_setprio 1
; #define G_MMA(ks_) __builtin_amdgcn_s_setprio(1); _Pragma("unroll") for (int m = 0; m < 4; ++m) \
;         _Pragma("unroll") for (int n = 0; n < 4; ++n) acc[m][n] = __builtin_amdgcn_mfma_f32_16x16x32_bf16(bfv##ks_[n], af##ks_[m], acc[m][n], 0, 0, 0); __builtin_amdgcn_s_setprio(0);
; template <class Epi>
; DEV void gemm_tile(const bf16_t* __restrict__ A, int lda, const bf16_t* __restrict__ Bt, int ldb, int K, int tm, int tn, char* smem, const Epi& epi) {
;     ...
;     const int nk = K >> 6;
;     G_DMA(0, 0);
;     asm volatile("s_waitcnt vmcnt(0)" ::: "memory");
;     __syncthreads();
; #pragma unroll 4
;     for (int kt = 0; kt < nk; ++kt) {
;         const int cur = kt & 1;
;         if (kt + 1 < nk) G_DMA(cur ^ 1, kt + 1);
;         {
;             G_FRAGS(cur, 0)
;             G_MMA(0)
;             G_FRAGS(cur, 1)
;             G_MMA(1)
;         }
;         asm volatile("s_waitcnt vmcnt(0)" ::: "memory");
;         __syncthreads();
;     }
.Lgemm_down_lowprio:
	s_movk_i32 s92, 21
.Lgemm_down_loop:
	ds_read_b128 v[158:161], v222
	ds_read_b128 v[164:167], v222 offset:2048
	ds_read_b128 v[168:171], v222 offset:4096
	ds_read_b128 v[172:175], v222 offset:6144
	ds_read_b128 v[176:179], v224 offset:32768
	ds_read_b128 v[180:183], v224 offset:34816
	ds_read_b128 v[192:195], v224 offset:36864
	ds_read_b128 v[210:213], v224 offset:38912
	s_waitcnt lgkmcnt(8)
	v_mfma_f32_16x16x32_bf16 v[62:65], v[142:145], v[126:129], v[62:65]
	v_mfma_f32_16x16x32_bf16 v[66:69], v[146:149], v[126:129], v[66:69]
	v_mfma_f32_16x16x32_bf16 v[70:73], v[150:153], v[126:129], v[70:73]
	v_mfma_f32_16x16x32_bf16 v[2:5], v[154:157], v[126:129], v[2:5]
	v_mfma_f32_16x16x32_bf16 v[14:17], v[142:145], v[130:133], v[14:17]
	v_mfma_f32_16x16x32_bf16 v[22:25], v[146:149], v[130:133], v[22:25]
	v_mfma_f32_16x16x32_bf16 v[30:33], v[150:153], v[130:133], v[30:33]
	v_mfma_f32_16x16x32_bf16 v[18:21], v[154:157], v[130:133], v[18:21]
	v_mfma_f32_16x16x32_bf16 v[26:29], v[142:145], v[134:137], v[26:29]
	v_mfma_f32_16x16x32_bf16 v[34:37], v[146:149], v[134:137], v[34:37]
	v_mfma_f32_16x16x32_bf16 v[58:61], v[150:153], v[134:137], v[58:61]
	v_mfma_f32_16x16x32_bf16 v[38:41], v[154:157], v[134:137], v[38:41]
	v_mfma_f32_16x16x32_bf16 v[46:49], v[142:145], v[138:141], v[46:49]
	v_mfma_f32_16x16x32_bf16 v[50:53], v[146:149], v[138:141], v[50:53]
	v_mfma_f32_16x16x32_bf16 v[54:57], v[150:153], v[138:141], v[54:57]
	v_mfma_f32_16x16x32_bf16 v[10:13], v[154:157], v[138:141], v[10:13]
	s_waitcnt vmcnt(0) lgkmcnt(0)
	s_barrier
	ds_read_b128 v[126:129], v221 offset:16384
	ds_read_b128 v[130:133], v221 offset:18432
	ds_read_b128 v[134:137], v221 offset:20480
	ds_read_b128 v[138:141], v221 offset:22528
	ds_read_b128 v[142:145], v223 offset:49152
	ds_read_b128 v[146:149], v223 offset:51200
	ds_read_b128 v[150:153], v223 offset:53248
	ds_read_b128 v[154:157], v223 offset:55296
	s_mov_b32 m0, s93
	v_mfma_f32_16x16x32_bf16 v[62:65], v[176:179], v[158:161], v[62:65]
	global_load_lds_dwordx4 v184, s[88:89]
	s_add_u32 m0, m0, 0x1000
	v_mfma_f32_16x16x32_bf16 v[66:69], v[180:183], v[158:161], v[66:69]
	global_load_lds_dwordx4 v214, s[88:89]
	s_add_u32 m0, m0, 0x1000
	v_mfma_f32_16x16x32_bf16 v[70:73], v[192:195], v[158:161], v[70:73]
	global_load_lds_dwordx4 v215, s[88:89]
	s_add_u32 m0, m0, 0x1000
	v_mfma_f32_16x16x32_bf16 v[2:5], v[210:213], v[158:161], v[2:5]
	global_load_lds_dwordx4 v216, s[88:89]
	s_add_u32 m0, m0, 0x5000
	v_mfma_f32_16x16x32_bf16 v[14:17], v[176:179], v[164:167], v[14:17]
	global_load_lds_dwordx4 v217, s[90:91]
	s_add_u32 m0, m0, 0x1000
	v_mfma_f32_16x16x32_bf16 v[22:25], v[180:183], v[164:167], v[22:25]
	global_load_lds_dwordx4 v218, s[90:91]
	s_add_u32 m0, m0, 0x1000
	v_mfma_f32_16x16x32_bf16 v[30:33], v[192:195], v[164:167], v[30:33]
	global_load_lds_dwordx4 v219, s[90:91]
	s_add_u32 m0, m0, 0x1000
	v_mfma_f32_16x16x32_bf16 v[18:21], v[210:213], v[164:167], v[18:21]
	global_load_lds_dwordx4 v220, s[90:91]
	v_mfma_f32_16x16x32_bf16 v[26:29], v[176:179], v[168:171], v[26:29]
	s_add_u32 s88, s88, 0x80
	v_mfma_f32_16x16x32_bf16 v[34:37], v[180:183], v[168:171], v[34:37]
	s_addc_u32 s89, s89, 0
	v_mfma_f32_16x16x32_bf16 v[58:61], v[192:195], v[168:171], v[58:61]
	s_add_u32 s90, s90, 0x80
	v_mfma_f32_16x16x32_bf16 v[38:41], v[210:213], v[168:171], v[38:41]
	s_addc_u32 s91, s91, 0
	v_mfma_f32_16x16x32_bf16 v[46:49], v[176:179], v[172:175], v[46:49]
	v_mfma_f32_16x16x32_bf16 v[50:53], v[180:183], v[172:175], v[50:53]
	v_mfma_f32_16x16x32_bf16 v[54:57], v[192:195], v[172:175], v[54:57]
	v_mfma_f32_16x16x32_bf16 v[10:13], v[210:213], v[172:175], v[10:13]
	ds_read_b128 v[158:161], v222 offset:16384
	ds_read_b128 v[164:167], v222 offset:18432
	ds_read_b128 v[168:171], v222 offset:20480
	ds_read_b128 v[172:175], v222 offset:22528
	ds_read_b128 v[176:179], v224 offset:49152
	ds_read_b128 v[180:183], v224 offset:51200
	ds_read_b128 v[192:195], v224 offset:53248
	ds_read_b128 v[210:213], v224 offset:55296
	s_waitcnt lgkmcnt(8)
	v_mfma_f32_16x16x32_bf16 v[62:65], v[142:145], v[126:129], v[62:65]
	v_mfma_f32_16x16x32_bf16 v[66:69], v[146:149], v[126:129], v[66:69]
	v_mfma_f32_16x16x32_bf16 v[70:73], v[150:153], v[126:129], v[70:73]
	v_mfma_f32_16x16x32_bf16 v[2:5], v[154:157], v[126:129], v[2:5]
	v_mfma_f32_16x16x32_bf16 v[14:17], v[142:145], v[130:133], v[14:17]
	v_mfma_f32_16x16x32_bf16 v[22:25], v[146:149], v[130:133], v[22:25]
	v_mfma_f32_16x16x32_bf16 v[30:33], v[150:153], v[130:133], v[30:33]
	v_mfma_f32_16x16x32_bf16 v[18:21], v[154:157], v[130:133], v[18:21]
	v_mfma_f32_16x16x32_bf16 v[26:29], v[142:145], v[134:137], v[26:29]
	v_mfma_f32_16x16x32_bf16 v[34:37], v[146:149], v[134:137], v[34:37]
	v_mfma_f32_16x16x32_bf16 v[58:61], v[150:153], v[134:137], v[58:61]
	v_mfma_f32_16x16x32_bf16 v[38:41], v[154:157], v[134:137], v[38:41]
	v_mfma_f32_16x16x32_bf16 v[46:49], v[142:145], v[138:141], v[46:49]
	v_mfma_f32_16x16x32_bf16 v[50:53], v[146:149], v[138:141], v[50:53]
	v_mfma_f32_16x16x32_bf16 v[54:57], v[150:153], v[138:141], v[54:57]
	v_mfma_f32_16x16x32_bf16 v[10:13], v[154:157], v[138:141], v[10:13]
	s_waitcnt vmcnt(0) lgkmcnt(0)
	s_barrier
; #define G_MMA(ks_) __builtin_amdgcn_s_setprio(1); _Pragma("unroll") for (int m = 0; m < 4; ++m) \
;         _Pragma("unroll") for (int n = 0; n < 4; ++n) acc[m][n] = __builtin_amdgcn_mfma_f32_16x16x32_bf16(bfv##ks_[n], af##ks_[m], acc[m][n], 0, 0, 0); __builtin_amdgcn_s_setprio(0);
; template <class Epi>
; DEV void gemm_tile(const bf16_t* __restrict__ A, int lda, const bf16_t* __restrict__ Bt, int ldb, int K, int tm, int tn, char* smem, const Epi& epi) {
;     ...
;     const int nk = K >> 6;
;     G_DMA(0, 0);
;     asm volatile("s_waitcnt vmcnt(0)" ::: "memory");
;     __syncthreads();
; #pragma unroll 4
;     for (int kt = 0; kt < nk; ++kt) {
;         const int cur = kt & 1;
;         if (kt + 1 < nk) G_DMA(cur ^ 1, kt + 1);
;         {
;             G_FRAGS(cur, 0)
;             G_MMA(0)
;             G_FRAGS(cur, 1)
;             G_MMA(1)
;         }
;         asm volatile("s_waitcnt vmcnt(0)" ::: "memory");
;         __syncthreads();
;     }
	ds_read_b128 v[126:129], v221
	ds_read_b128 v[130:133], v221 offset:2048
	ds_read_b128 v[134:137], v221 offset:4096
	ds_read_b128 v[138:141], v221 offset:6144
	ds_read_b128 v[142:145], v223 offset:32768
	ds_read_b128 v[146:149], v223 offset:34816
	ds_read_b128 v[150:153], v223 offset:36864
	ds_read_b128 v[154:157], v223 offset:38912
	s_mov_b32 m0, s94
	v_mfma_f32_16x16x32_bf16 v[62:65], v[176:179], v[158:161], v[62:65]
	global_load_lds_dwordx4 v184, s[88:89]
	s_add_u32 m0, m0, 0x1000
	v_mfma_f32_16x16x32_bf16 v[66:69], v[180:183], v[158:161], v[66:69]
	global_load_lds_dwordx4 v214, s[88:89]
	s_add_u32 m0, m0, 0x1000
	v_mfma_f32_16x16x32_bf16 v[70:73], v[192:195], v[158:161], v[70:73]
	global_load_lds_dwordx4 v215, s[88:89]
	s_add_u32 m0, m0, 0x1000
	v_mfma_f32_16x16x32_bf16 v[2:5], v[210:213], v[158:161], v[2:5]
	global_load_lds_dwordx4 v216, s[88:89]
	s_add_u32 m0, m0, 0x5000
	v_mfma_f32_16x16x32_bf16 v[14:17], v[176:179], v[164:167], v[14:17]
	global_load_lds_dwordx4 v217, s[90:91]
	s_add_u32 m0, m0, 0x1000
	v_mfma_f32_16x16x32_bf16 v[22:25], v[180:183], v[164:167], v[22:25]
	global_load_lds_dwordx4 v218, s[90:91]
	s_add_u32 m0, m0, 0x1000
	v_mfma_f32_16x16x32_bf16 v[30:33], v[192:195], v[164:167], v[30:33]
	global_load_lds_dwordx4 v219, s[90:91]
	s_add_u32 m0, m0, 0x1000
	v_mfma_f32_16x16x32_bf16 v[18:21], v[210:213], v[164:167], v[18:21]
	global_load_lds_dwordx4 v220, s[90:91]
	v_mfma_f32_16x16x32_bf16 v[26:29], v[176:179], v[168:171], v[26:29]
	s_add_u32 s88, s88, 0x80
	v_mfma_f32_16x16x32_bf16 v[34:37], v[180:183], v[168:171], v[34:37]
	s_addc_u32 s89, s89, 0
	v_mfma_f32_16x16x32_bf16 v[58:61], v[192:195], v[168:171], v[58:61]
	s_add_u32 s90, s90, 0x80
	v_mfma_f32_16x16x32_bf16 v[38:41], v[210:213], v[168:171], v[38:41]
	s_addc_u32 s91, s91, 0
	v_mfma_f32_16x16x32_bf16 v[46:49], v[176:179], v[172:175], v[46:49]
	v_mfma_f32_16x16x32_bf16 v[50:53], v[180:183], v[172:175], v[50:53]
	v_mfma_f32_16x16x32_bf16 v[54:57], v[192:195], v[172:175], v[54:57]
	v_mfma_f32_16x16x32_bf16 v[10:13], v[210:213], v[172:175], v[10:13]
	s_sub_u32 s92, s92, 1
	s_cmp_lg_u32 s92, 0
	s_cbranch_scc1 .Lgemm_down_loop
	ds_read_b128 v[158:161], v222
	ds_read_b128 v[164:167], v222 offset:2048
	ds_read_b128 v[168:171], v222 offset:4096
	ds_read_b128 v[172:175], v222 offset:6144
	ds_read_b128 v[176:179], v224 offset:32768
	ds_read_b128 v[180:183], v224 offset:34816
	ds_read_b128 v[192:195], v224 offset:36864
	ds_read_b128 v[210:213], v224 offset:38912
	s_waitcnt lgkmcnt(8)
	v_mfma_f32_16x16x32_bf16 v[62:65], v[142:145], v[126:129], v[62:65]
	v_mfma_f32_16x16x32_bf16 v[66:69], v[146:149], v[126:129], v[66:69]
	v_mfma_f32_16x16x32_bf16 v[70:73], v[150:153], v[126:129], v[70:73]
	v_mfma_f32_16x16x32_bf16 v[2:5], v[154:157], v[126:129], v[2:5]
	v_mfma_f32_16x16x32_bf16 v[14:17], v[142:145], v[130:133], v[14:17]
	v_mfma_f32_16x16x32_bf16 v[22:25], v[146:149], v[130:133], v[22:25]
	v_mfma_f32_16x16x32_bf16 v[30:33], v[150:153], v[130:133], v[30:33]
	v_mfma_f32_16x16x32_bf16 v[18:21], v[154:157], v[130:133], v[18:21]
	v_mfma_f32_16x16x32_bf16 v[26:29], v[142:145], v[134:137], v[26:29]
	v_mfma_f32_16x16x32_bf16 v[34:37], v[146:149], v[134:137], v[34:37]
	v_mfma_f32_16x16x32_bf16 v[58:61], v[150:153], v[134:137], v[58:61]
	v_mfma_f32_16x16x32_bf16 v[38:41], v[154:157], v[134:137], v[38:41]
	v_mfma_f32_16x16x32_bf16 v[46:49], v[142:145], v[138:141], v[46:49]
	v_mfma_f32_16x16x32_bf16 v[50:53], v[146:149], v[138:141], v[50:53]
	v_mfma_f32_16x16x32_bf16 v[54:57], v[150:153], v[138:141], v[54:57]
	v_mfma_f32_16x16x32_bf16 v[10:13], v[154:157], v[138:141], v[10:13]
	s_waitcnt vmcnt(0) lgkmcnt(0)
	s_barrier
	ds_read_b128 v[126:129], v221 offset:16384
	ds_read_b128 v[130:133], v221 offset:18432
	ds_read_b128 v[134:137], v221 offset:20480
	ds_read_b128 v[138:141], v221 offset:22528
	ds_read_b128 v[142:145], v223 offset:49152
	ds_read_b128 v[146:149], v223 offset:51200
	ds_read_b128 v[150:153], v223 offset:53248
	ds_read_b128 v[154:157], v223 offset:55296
	v_mfma_f32_16x16x32_bf16 v[62:65], v[176:179], v[158:161], v[62:65]
	v_mfma_f32_16x16x32_bf16 v[66:69], v[180:183], v[158:161], v[66:69]
	v_mfma_f32_16x16x32_bf16 v[70:73], v[192:195], v[158:161], v[70:73]
	v_mfma_f32_16x16x32_bf16 v[2:5], v[210:213], v[158:161], v[2:5]
	v_mfma_f32_16x16x32_bf16 v[14:17], v[176:179], v[164:167], v[14:17]
	v_mfma_f32_16x16x32_bf16 v[22:25], v[180:183], v[164:167], v[22:25]
	v_mfma_f32_16x16x32_bf16 v[30:33], v[192:195], v[164:167], v[30:33]
	v_mfma_f32_16x16x32_bf16 v[18:21], v[210:213], v[164:167], v[18:21]
	v_mfma_f32_16x16x32_bf16 v[26:29], v[176:179], v[168:171], v[26:29]
	v_mfma_f32_16x16x32_bf16 v[34:37], v[180:183], v[168:171], v[34:37]
	v_mfma_f32_16x16x32_bf16 v[58:61], v[192:195], v[168:171], v[58:61]
	v_mfma_f32_16x16x32_bf16 v[38:41], v[210:213], v[168:171], v[38:41]
	v_mfma_f32_16x16x32_bf16 v[46:49], v[176:179], v[172:175], v[46:49]
	v_mfma_f32_16x16x32_bf16 v[50:53], v[180:183], v[172:175], v[50:53]
	v_mfma_f32_16x16x32_bf16 v[54:57], v[192:195], v[172:175], v[54:57]
	v_mfma_f32_16x16x32_bf16 v[10:13], v[210:213], v[172:175], v[10:13]
	ds_read_b128 v[158:161], v222 offset:16384
	ds_read_b128 v[164:167], v222 offset:18432
	ds_read_b128 v[168:171], v222 offset:20480
	ds_read_b128 v[172:175], v222 offset:22528
	ds_read_b128 v[176:179], v224 offset:49152
	ds_read_b128 v[180:183], v224 offset:51200
	ds_read_b128 v[192:195], v224 offset:53248
	ds_read_b128 v[210:213], v224 offset:55296
	s_waitcnt lgkmcnt(8)
	v_mfma_f32_16x16x32_bf16 v[62:65], v[142:145], v[126:129], v[62:65]
	v_mfma_f32_16x16x32_bf16 v[66:69], v[146:149], v[126:129], v[66:69]
	v_mfma_f32_16x16x32_bf16 v[70:73], v[150:153], v[126:129], v[70:73]
	v_mfma_f32_16x16x32_bf16 v[2:5], v[154:157], v[126:129], v[2:5]
	v_mfma_f32_16x16x32_bf16 v[14:17], v[142:145], v[130:133], v[14:17]
	v_mfma_f32_16x16x32_bf16 v[22:25], v[146:149], v[130:133], v[22:25]
	v_mfma_f32_16x16x32_bf16 v[30:33], v[150:153], v[130:133], v[30:33]
	v_mfma_f32_16x16x32_bf16 v[18:21], v[154:157], v[130:133], v[18:21]
	v_mfma_f32_16x16x32_bf16 v[26:29], v[142:145], v[134:137], v[26:29]
	v_mfma_f32_16x16x32_bf16 v[34:37], v[146:149], v[134:137], v[34:37]
	v_mfma_f32_16x16x32_bf16 v[58:61], v[150:153], v[134:137], v[58:61]
	v_mfma_f32_16x16x32_bf16 v[38:41], v[154:157], v[134:137], v[38:41]
	v_mfma_f32_16x16x32_bf16 v[46:49], v[142:145], v[138:141], v[46:49]
	v_mfma_f32_16x16x32_bf16 v[50:53], v[146:149], v[138:141], v[50:53]
	v_mfma_f32_16x16x32_bf16 v[54:57], v[150:153], v[138:141], v[54:57]
	v_mfma_f32_16x16x32_bf16 v[10:13], v[154:157], v[138:141], v[10:13]
	s_waitcnt lgkmcnt(0)
	s_barrier
; DEV int tid_() { int t = __builtin_amdgcn_workitem_id_x(); asm volatile("" : "+v"(t)); return t; }
; #define G_MMA(ks_) __builtin_amdgcn_s_setprio(1); _Pragma("unroll") for (int m = 0; m < 4; ++m) \
;         _Pragma("unroll") for (int n = 0; n < 4; ++n) acc[m][n] = __builtin_amdgcn_mfma_f32_16x16x32_bf16(bfv##ks_[n], af##ks_[m], acc[m][n], 0, 0, 0); __builtin_amdgcn_s_setprio(0);
; template <class Epi>
; DEV void gemm_tile(const bf16_t* __restrict__ A, int lda, const bf16_t* __restrict__ Bt, int ldb, int K, int tm, int tn, char* smem, const Epi& epi) {
;     ...
;             G_MMA(1)
;         }
;         asm volatile("s_waitcnt vmcnt(0)" ::: "memory");
;         __syncthreads();
;     }
;     ...
;     float* Ct = (float*)smem;
; #pragma unroll
;     for (int m = 0; m < 4; ++m)
; #pragma unroll
;         for (int n = 0; n < 4; ++n) *(f32x4*)(Ct + (wr * 64 + m * 16 + fr) * CP + wc * 64 + n * 16 + fq * 4) = acc[m][n];
;     __syncthreads();
;     DEV void operator()(int tm, int tn, const float* Ct) const {
;         const int row0 = tm * 128, b = row0 / TT, tt0 = row0 - b * TT;
;         const int tid = tid_(), c = (tid & 31) << 2, rb = tid >> 5;
;         const f32x4 g = *(const f32x4*)(mod + (size_t)(tt0 < SEQ ? b : 32) * 6144 + goff + tn * 128 + c);
;         float* x0 = xrow(*p, row0) + tn * 128 + c;
;         const float* xs = from_in ? xrow_in(*p, row0) + tn * 128 + c : x0;
	v_mfma_f32_16x16x32_bf16 v[62:65], v[176:179], v[158:161], v[62:65]
	v_mfma_f32_16x16x32_bf16 v[66:69], v[180:183], v[158:161], v[66:69]
	v_mfma_f32_16x16x32_bf16 v[70:73], v[192:195], v[158:161], v[70:73]
	v_mfma_f32_16x16x32_bf16 v[2:5], v[210:213], v[158:161], v[2:5]
	v_mfma_f32_16x16x32_bf16 v[14:17], v[176:179], v[164:167], v[14:17]
	v_mfma_f32_16x16x32_bf16 v[22:25], v[180:183], v[164:167], v[22:25]
	v_mfma_f32_16x16x32_bf16 v[30:33], v[192:195], v[164:167], v[30:33]
	v_mfma_f32_16x16x32_bf16 v[18:21], v[210:213], v[164:167], v[18:21]
	v_mfma_f32_16x16x32_bf16 v[26:29], v[176:179], v[168:171], v[26:29]
	v_mfma_f32_16x16x32_bf16 v[34:37], v[180:183], v[168:171], v[34:37]
	v_mfma_f32_16x16x32_bf16 v[58:61], v[192:195], v[168:171], v[58:61]
	v_mfma_f32_16x16x32_bf16 v[38:41], v[210:213], v[168:171], v[38:41]
	v_mfma_f32_16x16x32_bf16 v[46:49], v[176:179], v[172:175], v[46:49]
	v_mfma_f32_16x16x32_bf16 v[50:53], v[180:183], v[172:175], v[50:53]
	v_mfma_f32_16x16x32_bf16 v[54:57], v[192:195], v[172:175], v[54:57]
	v_mfma_f32_16x16x32_bf16 v[10:13], v[210:213], v[172:175], v[10:13]
	s_setprio 0
	v_readlane_b32 s88, v255, 24
	v_readlane_b32 s89, v255, 25
	v_readlane_b32 s90, v255, 26
	v_readlane_b32 s91, v255, 27
	v_readlane_b32 s92, v255, 28
	v_readlane_b32 s93, v255, 29
	v_readlane_b32 s94, v255, 30
	v_readlane_b32 s95, v255, 31
	s_nop 7
	s_nop 1
	s_mul_hi_u32 s39, s39, 0x38e38e39
	s_lshr_b32 s46, s39, 2
	s_mul_i32 s39, s46, 0xfffff700
	s_add_i32 s47, s39, s38
	s_cmpk_lt_i32 s47, 0x800
	s_cselect_b64 s[38:39], -1, 0
	s_mul_i32 s43, s46, 0x6000
	s_and_b64 s[44:45], s[38:39], exec
	v_lshl_or_b32 v7, v8, 6, v7
	s_cselect_b32 s43, s43, 0xc0000
	v_lshl_add_u32 v6, v6, 8, 16
	v_lshlrev_b32_e32 v0, 4, v0
	v_mul_lo_u32 v7, v7, s58
	s_add_u32 s43, s10, s43
	v_add3_u32 v0, v6, v0, v7
	v_mov_b32_e32 v8, v163
	s_addc_u32 s44, s11, 0
	s_lshl_b32 s45, s42, 2
	s_waitcnt vmcnt(0)
	s_barrier
	ds_write_b128 v0, v[62:65]
	ds_write_b128 v0, v[66:69] offset:64
	ds_write_b128 v0, v[70:73] offset:128
	ds_write_b128 v0, v[2:5] offset:192
	ds_write_b128 v0, v[14:17] offset:8448
	ds_write_b128 v0, v[22:25] offset:8512
	ds_write_b128 v0, v[30:33] offset:8576
	ds_write_b128 v0, v[18:21] offset:8640
	ds_write_b128 v0, v[26:29] offset:16896
	ds_write_b128 v0, v[34:37] offset:16960
	ds_write_b128 v0, v[58:61] offset:17024
	ds_write_b128 v0, v[38:41] offset:17088
	ds_write_b128 v0, v[46:49] offset:25344
	ds_write_b128 v0, v[50:53] offset:25408
	ds_write_b128 v0, v[54:57] offset:25472
	ds_write_b128 v0, v[10:13] offset:25536
	s_waitcnt lgkmcnt(0)
	s_barrier
; DEV int tid_() { int t = __builtin_amdgcn_workitem_id_x(); asm volatile("" : "+v"(t)); return t; }
;     DEV void operator()(int tm, int tn, const float* Ct) const {
;         const int row0 = tm * 128, b = row0 / TT, tt0 = row0 - b * TT;
;         const int tid = tid_(), c = (tid & 31) << 2, rb = tid >> 5;
;         const f32x4 g = *(const f32x4*)(mod + (size_t)(tt0 < SEQ ? b : 32) * 6144 + goff + tn * 128 + c);
;         float* x0 = xrow(*p, row0) + tn * 128 + c;
;         const float* xs = from_in ? xrow_in(*p, row0) + tn * 128 + c : x0;
; #pragma unroll
;         for (int it0 = 0; it0 < 16; it0 += 8) {
;             f32x4 xv[8];
; #pragma unroll
;             for (int u = 0; u < 8; ++u) xv[u] = *(const f32x4*)(xs + (size_t)(rb + 8 * (it0 + u)) * D);
; #pragma unroll
;             for (int u = 0; u < 8; ++u) { const int r = rb + 8 * (it0 + u); *(f32x4*)(x0 + (size_t)r * D) = xv[u] + g * *(const f32x4*)(Ct + r * CP + c); }
;         }
	s_add_u32 s42, s43, s45
	v_lshlrev_b32_e32 v0, 4, v8
	s_addc_u32 s43, s44, 0
	v_and_b32_e32 v0, 0x1f0, v0
	v_lshl_add_u64 v[2:3], s[42:43], 0, v[0:1]
	s_movk_i32 s42, 0x5000
	v_add_co_u32_e32 v2, vcc, s42, v2
	s_add_i32 s42, s47, 0xfffff800
	s_ashr_i32 s43, s47, 31
	s_and_b64 s[38:39], s[38:39], exec
	v_readlane_b32 s48, v251, 1
	v_readlane_b32 s51, v251, 4
	v_readlane_b32 s38, v251, 36
	s_cselect_b32 s44, 23, 20
	v_readlane_b32 s49, v251, 2
	v_readlane_b32 s50, v251, 3
	s_cselect_b32 s48, s51, s38
	v_readlane_b32 s38, v251, 35
	s_cselect_b32 s49, s50, s38
	s_cselect_b32 s39, s43, 0
	s_cselect_b32 s38, s47, s42
	s_lshl_b32 s42, s46, s44
	s_add_u32 s42, s49, s42
	s_addc_u32 s43, s48, 0
	s_lshl_b64 s[38:39], s[38:39], 12
	s_add_u32 s38, s42, s38
	s_addc_u32 s39, s43, s39
	s_add_u32 s38, s38, s45
	v_ashrrev_i32_e32 v40, 5, v8
	s_addc_u32 s39, s39, 0
	v_ashrrev_i32_e32 v41, 31, v40
	v_lshl_add_u64 v[6:7], s[38:39], 0, v[0:1]
	v_lshlrev_b64 v[8:9], 12, v[40:41]
	v_addc_co_u32_e32 v3, vcc, 0, v3, vcc
	v_lshl_add_u64 v[6:7], v[6:7], 0, v[8:9]
	global_load_dwordx4 v[2:5], v[2:3], off
	s_mov_b32 s38, 0x8000
	global_load_dwordx4 v[8:11], v[6:7], off
	v_add_co_u32_e32 v44, vcc, s38, v6
	s_mov_b32 s38, 0x10000
	s_nop 0
	v_addc_co_u32_e32 v45, vcc, 0, v7, vcc
	global_load_dwordx4 v[12:15], v[44:45], off
	v_add_co_u32_e32 v46, vcc, s38, v6
	s_mov_b32 s38, 0x18000
	s_nop 0
	v_addc_co_u32_e32 v47, vcc, 0, v7, vcc
	global_load_dwordx4 v[16:19], v[46:47], off
	v_add_co_u32_e32 v48, vcc, s38, v6
	s_mov_b32 s38, 0x20000
	s_nop 0
	v_addc_co_u32_e32 v49, vcc, 0, v7, vcc
	global_load_dwordx4 v[20:23], v[48:49], off
	v_add_co_u32_e32 v50, vcc, s38, v6
	s_mov_b32 s38, 0x28000
	s_nop 0
	v_addc_co_u32_e32 v51, vcc, 0, v7, vcc
	global_load_dwordx4 v[24:27], v[50:51], off
	v_add_co_u32_e32 v52, vcc, s38, v6
	s_mov_b32 s38, 0x30000
	s_nop 0
	v_addc_co_u32_e32 v53, vcc, 0, v7, vcc
	global_load_dwordx4 v[28:31], v[52:53], off
	v_add_co_u32_e32 v54, vcc, s38, v6
	s_mov_b32 s38, 0x38000
	s_nop 0
	v_addc_co_u32_e32 v55, vcc, 0, v7, vcc
	global_load_dwordx4 v[32:35], v[54:55], off
	v_add_co_u32_e32 v56, vcc, s38, v6
	v_mul_lo_u32 v40, v40, s58
	s_nop 0
	v_addc_co_u32_e32 v57, vcc, 0, v7, vcc
	global_load_dwordx4 v[36:39], v[56:57], off
	v_add3_u32 v0, 16, v0, v40
	ds_read_b128 v[40:43], v0
	s_mov_b32 s38, 0x40000
	s_waitcnt vmcnt(7) lgkmcnt(0)
	v_pk_fma_f32 v[10:11], v[4:5], v[42:43], v[10:11]
	v_pk_fma_f32 v[8:9], v[2:3], v[40:41], v[8:9]
	global_store_dwordx4 v[6:7], v[8:11], off
	ds_read_b128 v[8:11], v0 offset:4224
	s_waitcnt vmcnt(7) lgkmcnt(0)
	v_pk_fma_f32 v[10:11], v[4:5], v[10:11], v[14:15]
	v_pk_fma_f32 v[8:9], v[2:3], v[8:9], v[12:13]
	global_store_dwordx4 v[44:45], v[8:11], off
	ds_read_b128 v[8:11], v0 offset:8448
	s_waitcnt vmcnt(7) lgkmcnt(0)
	v_pk_fma_f32 v[10:11], v[4:5], v[10:11], v[18:19]
	v_pk_fma_f32 v[8:9], v[2:3], v[8:9], v[16:17]
	global_store_dwordx4 v[46:47], v[8:11], off
	ds_read_b128 v[8:11], v0 offset:12672
	s_waitcnt vmcnt(7) lgkmcnt(0)
	v_pk_fma_f32 v[10:11], v[4:5], v[10:11], v[22:23]
	v_pk_fma_f32 v[8:9], v[2:3], v[8:9], v[20:21]
	global_store_dwordx4 v[48:49], v[8:11], off
	ds_read_b128 v[8:11], v0 offset:16896
	s_waitcnt vmcnt(7) lgkmcnt(0)
	v_pk_fma_f32 v[10:11], v[4:5], v[10:11], v[26:27]
	v_pk_fma_f32 v[8:9], v[2:3], v[8:9], v[24:25]
	global_store_dwordx4 v[50:51], v[8:11], off
	ds_read_b128 v[8:11], v0 offset:21120
	ds_read_b128 v[48:51], v0 offset:33792
	s_waitcnt vmcnt(7) lgkmcnt(1)
	v_pk_fma_f32 v[10:11], v[4:5], v[10:11], v[30:31]
	v_pk_fma_f32 v[8:9], v[2:3], v[8:9], v[28:29]
	global_store_dwordx4 v[52:53], v[8:11], off
	ds_read_b128 v[8:11], v0 offset:25344
	v_add_co_u32_e32 v52, vcc, s38, v6
	s_mov_b32 s38, 0x48000
	s_nop 0
	v_addc_co_u32_e32 v53, vcc, 0, v7, vcc
	s_waitcnt vmcnt(7) lgkmcnt(0)
	v_pk_fma_f32 v[10:11], v[4:5], v[10:11], v[34:35]
	v_pk_fma_f32 v[8:9], v[2:3], v[8:9], v[32:33]
	global_store_dwordx4 v[54:55], v[8:11], off
	ds_read_b128 v[8:11], v0 offset:29568
	v_add_co_u32_e32 v54, vcc, s38, v6
	s_mov_b32 s38, 0x50000
	s_nop 0
	v_addc_co_u32_e32 v55, vcc, 0, v7, vcc
	s_waitcnt vmcnt(7) lgkmcnt(0)
	v_pk_fma_f32 v[10:11], v[4:5], v[10:11], v[38:39]
	v_pk_fma_f32 v[8:9], v[2:3], v[8:9], v[36:37]
	global_load_dwordx4 v[36:39], v[52:53], off
	global_load_dwordx4 v[40:43], v[54:55], off
	s_nop 0
	global_store_dwordx4 v[56:57], v[8:11], off
	v_add_co_u32_e32 v56, vcc, s38, v6
	s_mov_b32 s38, 0x58000
	s_nop 0
	v_addc_co_u32_e32 v57, vcc, 0, v7, vcc
	global_load_dwordx4 v[44:47], v[56:57], off
	v_add_co_u32_e32 v34, vcc, s38, v6
	s_mov_b32 s38, 0x60000
	s_nop 0
	v_addc_co_u32_e32 v35, vcc, 0, v7, vcc
	global_load_dwordx4 v[22:25], v[34:35], off
	v_add_co_u32_e32 v32, vcc, s38, v6
	s_mov_b32 s38, 0x68000
	s_nop 0
	v_addc_co_u32_e32 v33, vcc, 0, v7, vcc
	global_load_dwordx4 v[18:21], v[32:33], off
	v_add_co_u32_e32 v30, vcc, s38, v6
	s_mov_b32 s38, 0x70000
	s_nop 0
	v_addc_co_u32_e32 v31, vcc, 0, v7, vcc
	global_load_dwordx4 v[14:17], v[30:31], off
	v_add_co_u32_e32 v28, vcc, s38, v6
	s_mov_b32 s38, 0x78000
	s_nop 0
	v_addc_co_u32_e32 v29, vcc, 0, v7, vcc
	global_load_dwordx4 v[10:13], v[28:29], off
	v_add_co_u32_e32 v26, vcc, s38, v6
	s_waitcnt vmcnt(7)
	v_pk_fma_f32 v[38:39], v[4:5], v[50:51], v[38:39]
	v_addc_co_u32_e32 v27, vcc, 0, v7, vcc
	global_load_dwordx4 v[6:9], v[26:27], off
	v_pk_fma_f32 v[36:37], v[2:3], v[48:49], v[36:37]
	global_store_dwordx4 v[52:53], v[36:39], off
	ds_read_b128 v[36:39], v0 offset:38016
	s_waitcnt vmcnt(8) lgkmcnt(0)
	v_pk_fma_f32 v[38:39], v[4:5], v[38:39], v[42:43]
	v_pk_fma_f32 v[36:37], v[2:3], v[36:37], v[40:41]
	global_store_dwordx4 v[54:55], v[36:39], off
	ds_read_b128 v[36:39], v0 offset:42240
	s_waitcnt vmcnt(7) lgkmcnt(0)
	v_pk_fma_f32 v[38:39], v[4:5], v[38:39], v[46:47]
	v_pk_fma_f32 v[36:37], v[2:3], v[36:37], v[44:45]
	global_store_dwordx4 v[56:57], v[36:39], off
	ds_read_b128 v[36:39], v0 offset:46464
	s_waitcnt vmcnt(7) lgkmcnt(0)
	v_pk_fma_f32 v[24:25], v[4:5], v[38:39], v[24:25]
	v_pk_fma_f32 v[22:23], v[2:3], v[36:37], v[22:23]
	global_store_dwordx4 v[34:35], v[22:25], off
	ds_read_b128 v[22:25], v0 offset:50688
	s_waitcnt vmcnt(7) lgkmcnt(0)
	v_pk_fma_f32 v[20:21], v[4:5], v[24:25], v[20:21]
	v_pk_fma_f32 v[18:19], v[2:3], v[22:23], v[18:19]
	global_store_dwordx4 v[32:33], v[18:21], off
	ds_read_b128 v[18:21], v0 offset:54912
	s_waitcnt vmcnt(7) lgkmcnt(0)
	v_pk_fma_f32 v[16:17], v[4:5], v[20:21], v[16:17]
	v_pk_fma_f32 v[14:15], v[2:3], v[18:19], v[14:15]
	global_store_dwordx4 v[30:31], v[14:17], off
	ds_read_b128 v[14:17], v0 offset:59136
	s_waitcnt vmcnt(7) lgkmcnt(0)
	v_pk_fma_f32 v[12:13], v[4:5], v[16:17], v[12:13]
	v_pk_fma_f32 v[10:11], v[2:3], v[14:15], v[10:11]
	global_store_dwordx4 v[28:29], v[10:13], off
	ds_read_b128 v[10:13], v0 offset:63360
	s_waitcnt vmcnt(7) lgkmcnt(0)
	v_pk_fma_f32 v[4:5], v[4:5], v[12:13], v[8:9]
	v_pk_fma_f32 v[2:3], v[2:3], v[10:11], v[6:7]
	global_store_dwordx4 v[26:27], v[2:5], off
	s_barrier
	s_branch .LBB0_178

; template <class Epi>
; DEV void gemm_tile(const bf16_t* __restrict__ A, int lda, const bf16_t* __restrict__ Bt, int ldb, int K, int tm, int tn, char* smem, const Epi& epi) {
;     ...
;     const int lrow = tid >> 3, lcc = (tid & 7) * 8, lsw = (((tid & 7) ^ (lrow & 7)) * 8);
;     const bf16_t* Ag = A + (size_t)(tm * 128 + lrow) * lda + lcc;
;     const bf16_t* Bg = Bt + (size_t)(tn * 128 + lrow) * ldb + lcc;
;     f32x4 acc[4][4];
; #pragma unroll
;     for (int m = 0; m < 4; ++m)
; #pragma unroll
;         for (int n = 0; n < 4; ++n) acc[m][n] = (f32x4){0.f, 0.f, 0.f, 0.f};
;     const int gsw = (((tid & 7) ^ (lrow & 7)) * 8);
;     const bf16_t* Ad = A + (size_t)(tm * 128 + lrow) * lda + gsw;
;     const bf16_t* Bd = Bt + (size_t)(tn * 128 + lrow) * ldb + gsw;
;     char* Asb = (char*)As; char* Bsb = (char*)Bs;
;     ...
;     const int nk = K >> 6;
;     G_DMA(0, 0);
;     asm volatile("s_waitcnt vmcnt(0)" ::: "memory");
;     __syncthreads();
; template <class Epi>
; DEV void gemm_phase(const bf16_t* A, int lda, const bf16_t* Bt, int ldb, int K, int ntm, int ntn, bool skip_ctx, char* smem, const Epi& epi) {
;     ...
;         for (int q = slot; q < per; q += nper) {
;             int tm, tn;
;             if (q < fullq) { const int tb = q / (R * 8), r = q - tb * (R * 8); tm = r >> 3; tn = tb * 8 + (r & 7); }
;             else { const int q2 = q - fullq; tm = q2 / w; tn = nfb * 8 + (q2 - tm * w); }
;             tm += xcd * R;
;             if (skip_ctx && ((tm * 128) % TT) >= SEQ) continue;
;             gemm_tile(A, lda, Bt, ldb, K, tm, tn, smem, epi);
.LBB0_683:
	v_readlane_b32 s0, v253, 32
	s_add_i32 s48, s2, s0
	v_mov_b32_e32 v12, v163
	s_lshl_b32 s51, s48, 7
	v_ashrrev_i32_e32 v14, 3, v12
	s_lshl_b32 s50, s62, 7
	v_add_u32_e32 v2, s51, v14
	v_add_u32_e32 v4, s50, v14
	v_ashrrev_i32_e32 v3, 31, v2
	v_ashrrev_i32_e32 v5, 31, v4
	s_waitcnt vmcnt(10)
	v_xor_b32_e32 v0, v14, v12
	v_lshlrev_b64 v[2:3], 11, v[2:3]
	v_lshlrev_b64 v[4:5], 11, v[4:5]
	v_lshlrev_b32_e32 v0, 4, v0
	v_lshl_add_u64 v[6:7], s[38:39], 0, v[2:3]
	v_lshl_add_u64 v[8:9], s[40:41], 0, v[4:5]
	v_and_b32_e32 v0, 0x70, v0
	v_lshl_add_u64 v[6:7], v[6:7], 0, v[0:1]
	v_lshl_add_u64 v[8:9], v[8:9], 0, v[0:1]
	v_lshlrev_b32_e32 v0, 4, v12
	v_add_u32_e32 v0, 16, v0
	v_add_u32_e32 v76, 0x8000, v0
	v_readfirstlane_b32 s0, v0
	s_mov_b32 m0, s0
	v_readfirstlane_b32 s0, v76
	v_add_u32_e32 v77, 0x1000, v0
	global_load_lds_dwordx4 v[6:7], off
	s_mov_b32 m0, s0
	s_mov_b64 s[2:3], 0x10000
	v_readfirstlane_b32 s0, v77
	v_add_u32_e32 v78, 0x9000, v0
	global_load_lds_dwordx4 v[8:9], off
	v_lshl_add_u64 v[10:11], v[6:7], 0, s[2:3]
	s_mov_b32 m0, s0
	v_readfirstlane_b32 s0, v78
	v_add_u32_e32 v79, 0x2000, v0
	global_load_lds_dwordx4 v[10:11], off
	v_lshl_add_u64 v[10:11], v[8:9], 0, s[2:3]
	s_mov_b32 m0, s0
	s_mov_b64 s[2:3], 0x20000
	v_readfirstlane_b32 s0, v79
	v_add_u32_e32 v80, 0xa000, v0
	global_load_lds_dwordx4 v[10:11], off
	v_lshl_add_u64 v[10:11], v[6:7], 0, s[2:3]
	s_mov_b32 m0, s0
	v_readfirstlane_b32 s0, v80
	v_add_u32_e32 v81, 0x3000, v0
	global_load_lds_dwordx4 v[10:11], off
	v_lshl_add_u64 v[10:11], v[8:9], 0, s[2:3]
	s_mov_b32 m0, s0
	s_mov_b64 s[2:3], 0x30000
	v_readfirstlane_b32 s0, v81
	v_add_u32_e32 v82, 0xb000, v0
	global_load_lds_dwordx4 v[10:11], off
	v_lshl_add_u64 v[6:7], v[6:7], 0, s[2:3]
	s_mov_b32 m0, s0
	v_readfirstlane_b32 s0, v82
	global_load_lds_dwordx4 v[6:7], off
	v_lshl_add_u64 v[6:7], v[8:9], 0, s[2:3]
	s_mov_b32 m0, s0
	v_lshrrev_b32_e32 v13, 4, v12
	global_load_lds_dwordx4 v[6:7], off
	v_and_b32_e32 v75, 15, v12
	v_ashrrev_i32_e32 v84, 7, v12
	v_bfe_u32 v83, v12, 4, 2
	v_and_b32_e32 v8, 7, v12
	v_lshlrev_b32_e32 v6, 13, v84
	v_lshlrev_b32_e32 v7, 7, v75
	v_bitop3_b32 v9, v13, v8, 3 bitop3:0x6c
	v_bitop3_b32 v8, v83, v8, 4 bitop3:0x36
	v_add3_u32 v6, 16, v6, v7
	v_lshlrev_b32_e32 v9, 4, v9
	v_lshlrev_b32_e32 v8, 4, v8
	v_add_u32_e32 v85, v6, v9
	v_add_u32_e32 v87, v6, v8
	v_bitop3_b32 v6, v14, 7, v12 bitop3:0x48
	v_bfe_u32 v74, v12, 6, 1
	v_lshlrev_b32_e32 v6, 4, v6
	s_waitcnt vmcnt(0)
	v_lshlrev_b32_e32 v10, 13, v74
	v_or_b32_e32 v2, v2, v6
	v_add3_u32 v7, 16, v10, v7
	v_or_b32_e32 v4, v4, v6
	v_lshl_add_u64 v[68:69], s[44:45], 0, v[2:3]
	v_mov_b32_e32 v2, 0
	v_add_u32_e32 v86, v7, v9
	v_add_u32_e32 v88, v7, v8
	v_lshl_add_u64 v[66:67], s[42:43], 0, v[4:5]
	s_mov_b64 s[0:1], 0
	v_mov_b32_e32 v3, v2
	v_mov_b32_e32 v4, v2
	v_mov_b32_e32 v5, v2
	v_mov_b32_e32 v6, v2
	v_mov_b32_e32 v7, v2
	v_mov_b32_e32 v8, v2
	v_mov_b32_e32 v9, v2
	v_mov_b32_e32 v10, v2
	v_mov_b32_e32 v11, v2
	v_mov_b32_e32 v12, v2
	v_mov_b32_e32 v13, v2
	v_mov_b32_e32 v14, v2
	v_mov_b32_e32 v15, v2
	v_mov_b32_e32 v16, v2
	v_mov_b32_e32 v17, v2
	s_waitcnt vmcnt(0)
	v_mov_b32_e32 v18, v2
	v_mov_b32_e32 v19, v2
	v_mov_b32_e32 v20, v2
	v_mov_b32_e32 v21, v2
	v_mov_b32_e32 v22, v2
	v_mov_b32_e32 v23, v2
	v_mov_b32_e32 v24, v2
	v_mov_b32_e32 v25, v2
	s_waitcnt vmcnt(0)
	v_mov_b32_e32 v26, v2
	v_mov_b32_e32 v27, v2
	v_mov_b32_e32 v28, v2
	v_mov_b32_e32 v29, v2
	v_mov_b32_e32 v30, v2
	v_mov_b32_e32 v31, v2
	v_mov_b32_e32 v32, v2
	v_mov_b32_e32 v33, v2
	v_mov_b32_e32 v34, v2
	v_mov_b32_e32 v35, v2
	v_mov_b32_e32 v36, v2
	v_mov_b32_e32 v37, v2
	v_mov_b32_e32 v38, v2
	v_mov_b32_e32 v39, v2
	v_mov_b32_e32 v40, v2
	v_mov_b32_e32 v41, v2
	v_mov_b32_e32 v42, v2
	v_mov_b32_e32 v43, v2
	v_mov_b32_e32 v44, v2
	v_mov_b32_e32 v45, v2
	v_mov_b32_e32 v46, v2
	v_mov_b32_e32 v47, v2
	v_mov_b32_e32 v48, v2
	v_mov_b32_e32 v49, v2
	v_mov_b32_e32 v50, v2
	v_mov_b32_e32 v51, v2
	v_mov_b32_e32 v52, v2
	v_mov_b32_e32 v53, v2
	v_mov_b32_e32 v54, v2
	v_mov_b32_e32 v55, v2
	v_mov_b32_e32 v56, v2
	v_mov_b32_e32 v57, v2
	v_mov_b32_e32 v58, v2
	v_mov_b32_e32 v59, v2
	v_mov_b32_e32 v60, v2
	v_mov_b32_e32 v61, v2
	v_mov_b32_e32 v62, v2
	v_mov_b32_e32 v63, v2
	v_mov_b32_e32 v64, v2
	v_mov_b32_e32 v65, v2
	s_waitcnt lgkmcnt(0)
	s_barrier
	v_writelane_b32 v255, s88, 24
	v_writelane_b32 v255, s89, 25
	v_writelane_b32 v255, s90, 26
	v_writelane_b32 v255, s91, 27
	v_writelane_b32 v255, s92, 28
	v_writelane_b32 v255, s93, 29
	v_writelane_b32 v255, s94, 30
	v_writelane_b32 v255, s95, 31
	v_readfirstlane_b32 s88, v68
	v_readfirstlane_b32 s89, v69
	v_readfirstlane_b32 s90, v66
	v_readfirstlane_b32 s91, v67
	v_lshl_add_u32 v161, v163, 4, 16
	s_and_b32 s88, s88, 0xffffff80
	s_and_b32 s90, s90, 0xffffff80
	v_readfirstlane_b32 s93, v161
	v_subrev_u32_e32 v89, s88, v68
	v_subrev_u32_e32 v153, s90, v66
	v_add_u32_e32 v150, 0x10000, v89
	v_add_u32_e32 v154, 0x10000, v153
	v_add_u32_e32 v151, 0x20000, v89
	v_add_u32_e32 v155, 0x20000, v153
	v_add_u32_e32 v152, 0x30000, v89
	v_add_u32_e32 v156, 0x30000, v153
	s_add_u32 s94, s93, 0x4000
	s_add_u32 s88, s88, 0x8688080
	s_addc_u32 s89, s89, 0
	s_add_u32 s90, s90, 0x23a8080
	s_addc_u32 s91, s91, 0
	v_and_b32_e32 v161, 15, v163
	v_lshlrev_b32_e32 v161, 7, v161
	v_bfe_u32 v164, v163, 4, 2
	v_and_b32_e32 v165, 7, v163
	v_xor_b32_e32 v164, v164, v165
	v_lshlrev_b32_e32 v165, 4, v164
	v_xor_b32_e32 v164, 4, v164
	v_lshlrev_b32_e32 v164, 4, v164
	v_lshrrev_b32_e32 v157, 7, v163
	v_lshl_add_u32 v157, v157, 13, v161
	v_add_u32_e32 v157, 16, v157
	v_bfe_u32 v159, v163, 6, 1
	v_lshl_add_u32 v159, v159, 13, v161
	v_add_u32_e32 v159, 16, v159
	v_add_u32_e32 v158, v157, v164
	v_add_u32_e32 v160, v159, v164
	v_add_u32_e32 v157, v157, v165
	v_add_u32_e32 v159, v159, v165
	s_mov_b32 m0, s94
	s_nop 0
	global_load_lds_dwordx4 v89, s[88:89]
	s_add_u32 m0, m0, 0x1000
	s_nop 0
	global_load_lds_dwordx4 v150, s[88:89]
	s_add_u32 m0, m0, 0x1000
	s_nop 0
	global_load_lds_dwordx4 v151, s[88:89]
	s_add_u32 m0, m0, 0x1000
	s_nop 0
	global_load_lds_dwordx4 v152, s[88:89]
	s_add_u32 m0, m0, 0x5000
	s_nop 0
	global_load_lds_dwordx4 v153, s[90:91]
	s_add_u32 m0, m0, 0x1000
	s_nop 0
	global_load_lds_dwordx4 v154, s[90:91]
	s_add_u32 m0, m0, 0x1000
	s_nop 0
	global_load_lds_dwordx4 v155, s[90:91]
	s_add_u32 m0, m0, 0x1000
	s_nop 0
	global_load_lds_dwordx4 v156, s[90:91]
	s_add_u32 s88, s88, 0x80
	s_addc_u32 s89, s89, 0
	s_add_u32 s90, s90, 0x80
	s_addc_u32 s91, s91, 0
	ds_read_b128 v[70:73], v157
	ds_read_b128 v[90:93], v157 offset:2048
	ds_read_b128 v[94:97], v157 offset:4096
	ds_read_b128 v[98:101], v157 offset:6144
	ds_read_b128 v[102:105], v159 offset:32768
	ds_read_b128 v[106:109], v159 offset:34816
	ds_read_b128 v[110:113], v159 offset:36864
	ds_read_b128 v[114:117], v159 offset:38912
	v_readlane_b32 s95, v251, 0
	s_nop 0
	s_cmp_lt_u32 s95, 0x100
	s_cbranch_scc1 .Lgemm_in_lowprio
	s_setprio 1
